# GEMM K-loops (P1/P5/P6): removed the dead issue slots inside MFMA-paced segments: mid-segment s_setprio 0/1 flip pair and the lgkmcnt(0) wait repeated after the barrier; on top of v23
# baseline (speedup 1.0000x reference)
; #define PG8_STAGE(bufoff, gbase, voff) do { _Pragma("unroll") for (int _i = 0; _i < 2; ++_i) \
;         __builtin_amdgcn_global_load_lds((const unsigned*)((const char*)(gbase) + (voff)[_i]), (PG8_LAS unsigned*)(lds + (bufoff) + ldsw + _i * 8192), 16, 0, 0); } while (0)
; #define PG8_LDA(dst, b, h) do { _Pragma("unroll") for (int m = 0; m < 4; ++m) _Pragma("unroll") for (int k = 0; k < 2; ++k) dst[m][k] = *(const PG8_LAS bf16x8*)(lds + PG8_SA(b, h) + aoff + m * 2048 + k * 1024); } while (0)
; #define PG8_LDB(dst, b, h) do { _Pragma("unroll") for (int n = 0; n < 2; ++n) _Pragma("unroll") for (int k = 0; k < 2; ++k) dst[n][k] = *(const PG8_LAS bf16x8*)(lds + PG8_SB(b, h) + boff + n * 2048 + k * 1024); } while (0)
; #define PG8_MMA(ai, bj, At, Bt) do { __builtin_amdgcn_s_setprio(1); _Pragma("unroll") for (int m = 0; m < 4; ++m) _Pragma("unroll") for (int n = 0; n < 2; ++n) _Pragma("unroll") for (int k = 0; k < 2; ++k) \
;         acc[ai][bj][m][n] = __builtin_amdgcn_mfma_f32_16x16x32_bf16(Bt[n][k], At[m][k], acc[ai][bj][m][n], 0, 0, 0); __builtin_amdgcn_s_setprio(0); } while (0)
; #define PG8_WAIT_V(n) asm volatile("s_waitcnt vmcnt(" #n ")" ::: "memory")
; #define PG8_WAIT_L(n) asm volatile("s_waitcnt lgkmcnt(" #n ")" ::: "memory")
; #define PG8_BAR __builtin_amdgcn_s_barrier()
; #define PG8_SCHED __builtin_amdgcn_sched_barrier(0)
; template <class Epi, class Sched, bool ALIGN_EPI = false, bool SP2 = false>
; __device__ __forceinline__ void gemm_phase(PG8_LAS unsigned char* lds, const Gemm g, const Sched& S, const Epi& E, int wid_in) {
;     ...
;             PG8_LDB(B0, 0, 0); PG8_LDB(B1, 0, 1); PG8_SCHED; PG8_LDA(At, 0, 0); PG8_STAGE(PG8_SA(1, 1), a1 + hstep, voffA);
;             PG8_WAIT_V(8); PG8_WAIT_L(0); PG8_BAR; PG8_MMA(0, 0, At, B0); PG8_MMA(0, 1, At, B1); PG8_BAR; PG8_SCHED;
;             PG8_LDA(At, 0, 1); PG8_STAGE(PG8_SB(0, 0), b2, voffB); PG8_STAGE(PG8_SB(0, 1), b2 + hstep, voffB); PG8_STAGE(PG8_SA(0, 0), a2, voffA);
.LBB0_227:
	ds_read_b128 v[128:131], v171
	ds_read_b128 v[132:135], v171 offset:1024
	ds_read_b128 v[158:161], v171 offset:2048
	ds_read_b128 v[162:165], v171 offset:3072
	ds_read_b128 v[174:177], v172
	ds_read_b128 v[178:181], v172 offset:1024
	ds_read_b128 v[182:185], v172 offset:2048
	ds_read_b128 v[186:189], v172 offset:3072
	s_add_u32 s88, s68, 0xfffc0080
	s_addc_u32 s89, s69, -1
	s_cmp_eq_u32 s94, 12
	s_cselect_b32 s91, s3, s89
	s_cselect_b32 s90, s5, s88
	s_cselect_b32 s89, s81, s93
	s_cselect_b32 s88, s83, s92
	v_lshl_add_u64 v[166:167], s[68:69], 0, v[150:151]
	s_add_i32 m0, s34, 0xc000
	ds_read_b128 v[190:193], v173
	ds_read_b128 v[194:197], v173 offset:1024
	ds_read_b128 v[198:201], v173 offset:2048
	ds_read_b128 v[202:205], v173 offset:3072
	ds_read_b128 v[206:209], v173 offset:4096
	ds_read_b128 v[210:213], v173 offset:5120
	ds_read_b128 v[214:217], v173 offset:6144
	ds_read_b128 v[218:221], v173 offset:7168
	global_load_lds_dwordx4 v[166:167], off
	v_lshl_add_u64 v[166:167], s[68:69], 0, v[152:153]
	s_add_i32 m0, s34, 0xe000
	s_nop 0
	global_load_lds_dwordx4 v[166:167], off
	s_waitcnt vmcnt(8)
	s_waitcnt lgkmcnt(0)
	s_barrier
	s_setprio 1
	v_mfma_f32_16x16x32_bf16 v[124:127], v[128:131], v[190:193], v[124:127]
	v_mfma_f32_16x16x32_bf16 v[120:123], v[158:161], v[190:193], v[120:123]
	v_mfma_f32_16x16x32_bf16 v[108:111], v[128:131], v[198:201], v[108:111]
	v_mfma_f32_16x16x32_bf16 v[104:107], v[158:161], v[198:201], v[104:107]
	v_mfma_f32_16x16x32_bf16 v[92:95], v[128:131], v[206:209], v[92:95]
	v_mfma_f32_16x16x32_bf16 v[88:91], v[158:161], v[206:209], v[88:91]
	v_mfma_f32_16x16x32_bf16 v[76:79], v[128:131], v[214:217], v[76:79]
	v_mfma_f32_16x16x32_bf16 v[72:75], v[158:161], v[214:217], v[72:75]
	v_mfma_f32_16x16x32_bf16 v[124:127], v[132:135], v[194:197], v[124:127]
	v_mfma_f32_16x16x32_bf16 v[120:123], v[162:165], v[194:197], v[120:123]
	v_mfma_f32_16x16x32_bf16 v[108:111], v[132:135], v[202:205], v[108:111]
	v_mfma_f32_16x16x32_bf16 v[104:107], v[162:165], v[202:205], v[104:107]
	v_mfma_f32_16x16x32_bf16 v[92:95], v[132:135], v[210:213], v[92:95]
	v_mfma_f32_16x16x32_bf16 v[88:91], v[162:165], v[210:213], v[88:91]
	v_mfma_f32_16x16x32_bf16 v[76:79], v[132:135], v[218:221], v[76:79]
	v_mfma_f32_16x16x32_bf16 v[72:75], v[162:165], v[218:221], v[72:75]
	v_mfma_f32_16x16x32_bf16 v[116:119], v[174:177], v[190:193], v[116:119]
	v_mfma_f32_16x16x32_bf16 v[112:115], v[182:185], v[190:193], v[112:115]
	v_mfma_f32_16x16x32_bf16 v[100:103], v[174:177], v[198:201], v[100:103]
	v_mfma_f32_16x16x32_bf16 v[96:99], v[182:185], v[198:201], v[96:99]
	v_mfma_f32_16x16x32_bf16 v[84:87], v[174:177], v[206:209], v[84:87]
	v_mfma_f32_16x16x32_bf16 v[80:83], v[182:185], v[206:209], v[80:83]
	v_mfma_f32_16x16x32_bf16 v[68:71], v[174:177], v[214:217], v[68:71]
	v_mfma_f32_16x16x32_bf16 v[64:67], v[182:185], v[214:217], v[64:67]
	v_mfma_f32_16x16x32_bf16 v[116:119], v[178:181], v[194:197], v[116:119]
	v_mfma_f32_16x16x32_bf16 v[112:115], v[186:189], v[194:197], v[112:115]
	v_mfma_f32_16x16x32_bf16 v[100:103], v[178:181], v[202:205], v[100:103]
	v_mfma_f32_16x16x32_bf16 v[96:99], v[186:189], v[202:205], v[96:99]
	v_mfma_f32_16x16x32_bf16 v[84:87], v[178:181], v[210:213], v[84:87]
	v_mfma_f32_16x16x32_bf16 v[80:83], v[186:189], v[210:213], v[80:83]
	v_mfma_f32_16x16x32_bf16 v[68:71], v[178:181], v[218:221], v[68:71]
	v_mfma_f32_16x16x32_bf16 v[64:67], v[186:189], v[218:221], v[64:67]
	s_setprio 0
	s_barrier
	s_add_i32 s95, s70, s12
	v_lshl_add_u64 v[166:167], s[88:89], 0, v[138:139]
	s_mov_b32 m0, s95
	ds_read_b128 v[190:193], v173 offset:16384
	ds_read_b128 v[194:197], v173 offset:17408
	ds_read_b128 v[198:201], v173 offset:18432
	ds_read_b128 v[202:205], v173 offset:19456
	ds_read_b128 v[206:209], v173 offset:20480
	ds_read_b128 v[210:213], v173 offset:21504
	ds_read_b128 v[214:217], v173 offset:22528
	ds_read_b128 v[218:221], v173 offset:23552
	global_load_lds_dwordx4 v[166:167], off
	s_add_i32 m0, s95, 0x2000
	s_add_u32 vcc_lo, s88, 0x40000
	v_lshl_add_u64 v[222:223], s[88:89], 0, v[142:143]
	s_addc_u32 vcc_hi, s89, 0
	s_add_i32 s95, s71, s12
	global_load_lds_dwordx4 v[222:223], off
	v_lshl_add_u64 v[224:225], vcc, 0, v[138:139]
	s_mov_b32 m0, s95
	v_lshl_add_u64 v[226:227], s[90:91], 0, v[140:141]
	global_load_lds_dwordx4 v[224:225], off
	v_lshl_add_u64 v[224:225], vcc, 0, v[142:143]
	s_add_i32 m0, s95, 0x2000
	s_nop 0
	global_load_lds_dwordx4 v[224:225], off
	v_lshl_add_u64 v[224:225], s[90:91], 0, v[136:137]
	s_mov_b32 m0, s34
	s_nop 0
	global_load_lds_dwordx4 v[224:225], off
	s_mov_b32 m0, s35
	s_nop 0
	global_load_lds_dwordx4 v[226:227], off
	s_waitcnt vmcnt(8)
	s_waitcnt lgkmcnt(0)
	s_barrier
; #define PG8_STAGE(bufoff, gbase, voff) do { _Pragma("unroll") for (int _i = 0; _i < 2; ++_i) \
;         __builtin_amdgcn_global_load_lds((const unsigned*)((const char*)(gbase) + (voff)[_i]), (PG8_LAS unsigned*)(lds + (bufoff) + ldsw + _i * 8192), 16, 0, 0); } while (0)
; #define PG8_LDA(dst, b, h) do { _Pragma("unroll") for (int m = 0; m < 4; ++m) _Pragma("unroll") for (int k = 0; k < 2; ++k) dst[m][k] = *(const PG8_LAS bf16x8*)(lds + PG8_SA(b, h) + aoff + m * 2048 + k * 1024); } while (0)
; #define PG8_LDB(dst, b, h) do { _Pragma("unroll") for (int n = 0; n < 2; ++n) _Pragma("unroll") for (int k = 0; k < 2; ++k) dst[n][k] = *(const PG8_LAS bf16x8*)(lds + PG8_SB(b, h) + boff + n * 2048 + k * 1024); } while (0)
; #define PG8_MMA(ai, bj, At, Bt) do { __builtin_amdgcn_s_setprio(1); _Pragma("unroll") for (int m = 0; m < 4; ++m) _Pragma("unroll") for (int n = 0; n < 2; ++n) _Pragma("unroll") for (int k = 0; k < 2; ++k) \
;         acc[ai][bj][m][n] = __builtin_amdgcn_mfma_f32_16x16x32_bf16(Bt[n][k], At[m][k], acc[ai][bj][m][n], 0, 0, 0); __builtin_amdgcn_s_setprio(0); } while (0)
; #define PG8_WAIT_V(n) asm volatile("s_waitcnt vmcnt(" #n ")" ::: "memory")
; #define PG8_WAIT_L(n) asm volatile("s_waitcnt lgkmcnt(" #n ")" ::: "memory")
; #define PG8_BAR __builtin_amdgcn_s_barrier()
; #define PG8_SCHED __builtin_amdgcn_sched_barrier(0)
; template <class Epi, class Sched, bool ALIGN_EPI = false, bool SP2 = false>
; __device__ __forceinline__ void gemm_phase(PG8_LAS unsigned char* lds, const Gemm g, const Sched& S, const Epi& E, int wid_in) {
;     ...
;             PG8_WAIT_V(8); PG8_WAIT_L(0); PG8_BAR; PG8_MMA(1, 0, At, B0); PG8_MMA(1, 1, At, B1); PG8_BAR; PG8_SCHED;
;             PG8_LDB(B0, 1, 0); PG8_LDB(B1, 1, 1); PG8_SCHED; PG8_LDA(At, 1, 0); PG8_STAGE(PG8_SA(0, 1), a2 + hstep, voffA);
;             PG8_WAIT_V(8); PG8_WAIT_L(0); PG8_BAR; PG8_MMA(0, 0, At, B0); PG8_MMA(0, 1, At, B1); PG8_BAR; PG8_SCHED;
	s_setprio 1
	v_mfma_f32_16x16x32_bf16 v[60:63], v[128:131], v[190:193], v[60:63]
	v_mfma_f32_16x16x32_bf16 v[56:59], v[158:161], v[190:193], v[56:59]
	v_mfma_f32_16x16x32_bf16 v[44:47], v[128:131], v[198:201], v[44:47]
	v_mfma_f32_16x16x32_bf16 v[40:43], v[158:161], v[198:201], v[40:43]
	v_mfma_f32_16x16x32_bf16 v[28:31], v[128:131], v[206:209], v[28:31]
	v_mfma_f32_16x16x32_bf16 v[24:27], v[158:161], v[206:209], v[24:27]
	v_mfma_f32_16x16x32_bf16 v[12:15], v[128:131], v[214:217], v[12:15]
	v_mfma_f32_16x16x32_bf16 v[8:11], v[158:161], v[214:217], v[8:11]
	v_mfma_f32_16x16x32_bf16 v[60:63], v[132:135], v[194:197], v[60:63]
	v_mfma_f32_16x16x32_bf16 v[56:59], v[162:165], v[194:197], v[56:59]
	v_mfma_f32_16x16x32_bf16 v[44:47], v[132:135], v[202:205], v[44:47]
	v_mfma_f32_16x16x32_bf16 v[40:43], v[162:165], v[202:205], v[40:43]
	v_mfma_f32_16x16x32_bf16 v[28:31], v[132:135], v[210:213], v[28:31]
	v_mfma_f32_16x16x32_bf16 v[24:27], v[162:165], v[210:213], v[24:27]
	v_mfma_f32_16x16x32_bf16 v[12:15], v[132:135], v[218:221], v[12:15]
	v_mfma_f32_16x16x32_bf16 v[8:11], v[162:165], v[218:221], v[8:11]
	v_mfma_f32_16x16x32_bf16 v[52:55], v[174:177], v[190:193], v[52:55]
	v_mfma_f32_16x16x32_bf16 v[48:51], v[182:185], v[190:193], v[48:51]
	v_mfma_f32_16x16x32_bf16 v[36:39], v[174:177], v[198:201], v[36:39]
	v_mfma_f32_16x16x32_bf16 v[32:35], v[182:185], v[198:201], v[32:35]
	v_mfma_f32_16x16x32_bf16 v[20:23], v[174:177], v[206:209], v[20:23]
	v_mfma_f32_16x16x32_bf16 v[16:19], v[182:185], v[206:209], v[16:19]
	v_mfma_f32_16x16x32_bf16 v[4:7], v[174:177], v[214:217], v[4:7]
	v_mfma_f32_16x16x32_bf16 v[0:3], v[182:185], v[214:217], v[0:3]
	v_mfma_f32_16x16x32_bf16 v[52:55], v[178:181], v[194:197], v[52:55]
	v_mfma_f32_16x16x32_bf16 v[48:51], v[186:189], v[194:197], v[48:51]
	v_mfma_f32_16x16x32_bf16 v[36:39], v[178:181], v[202:205], v[36:39]
	v_mfma_f32_16x16x32_bf16 v[32:35], v[186:189], v[202:205], v[32:35]
	v_mfma_f32_16x16x32_bf16 v[20:23], v[178:181], v[210:213], v[20:23]
	v_mfma_f32_16x16x32_bf16 v[16:19], v[186:189], v[210:213], v[16:19]
	v_mfma_f32_16x16x32_bf16 v[4:7], v[178:181], v[218:221], v[4:7]
	v_mfma_f32_16x16x32_bf16 v[0:3], v[186:189], v[218:221], v[0:3]
	s_setprio 0
	s_barrier
	s_add_i32 s95, 0, 0x18000
	v_add_u32_e32 v144, s95, v169
	s_add_i32 vcc_lo, 0, 0x1c000
	ds_read_b128 v[128:131], v144
	ds_read_b128 v[132:135], v144 offset:1024
	ds_read_b128 v[158:161], v144 offset:2048
	ds_read_b128 v[162:165], v144 offset:3072
	v_add_u32_e32 v144, vcc_lo, v169
	ds_read_b128 v[174:177], v144
	ds_read_b128 v[178:181], v144 offset:1024
	ds_read_b128 v[182:185], v144 offset:2048
	ds_read_b128 v[186:189], v144 offset:3072
	s_add_u32 s90, s90, 0x40000
	s_addc_u32 s91, s91, 0
	s_mov_b32 m0, s61
	v_lshl_add_u64 v[228:229], s[90:91], 0, v[136:137]
	ds_read_b128 v[190:193], v173 offset:32768
	ds_read_b128 v[194:197], v173 offset:33792
	ds_read_b128 v[198:201], v173 offset:34816
	ds_read_b128 v[202:205], v173 offset:35840
	ds_read_b128 v[206:209], v173 offset:36864
	ds_read_b128 v[210:213], v173 offset:37888
	ds_read_b128 v[214:217], v173 offset:38912
	ds_read_b128 v[218:221], v173 offset:39936
	global_load_lds_dwordx4 v[228:229], off
	v_lshl_add_u64 v[228:229], s[90:91], 0, v[140:141]
	s_mov_b32 m0, s62
	s_nop 0
	global_load_lds_dwordx4 v[228:229], off
	s_waitcnt vmcnt(8)
	s_waitcnt lgkmcnt(0)
	s_barrier
	s_setprio 1
	v_mfma_f32_16x16x32_bf16 v[124:127], v[128:131], v[190:193], v[124:127]
	v_mfma_f32_16x16x32_bf16 v[120:123], v[158:161], v[190:193], v[120:123]
	v_mfma_f32_16x16x32_bf16 v[108:111], v[128:131], v[198:201], v[108:111]
	v_mfma_f32_16x16x32_bf16 v[104:107], v[158:161], v[198:201], v[104:107]
	v_mfma_f32_16x16x32_bf16 v[92:95], v[128:131], v[206:209], v[92:95]
	v_mfma_f32_16x16x32_bf16 v[88:91], v[158:161], v[206:209], v[88:91]
	v_mfma_f32_16x16x32_bf16 v[76:79], v[128:131], v[214:217], v[76:79]
	v_mfma_f32_16x16x32_bf16 v[72:75], v[158:161], v[214:217], v[72:75]
	v_mfma_f32_16x16x32_bf16 v[124:127], v[132:135], v[194:197], v[124:127]
	v_mfma_f32_16x16x32_bf16 v[120:123], v[162:165], v[194:197], v[120:123]
	v_mfma_f32_16x16x32_bf16 v[108:111], v[132:135], v[202:205], v[108:111]
	v_mfma_f32_16x16x32_bf16 v[104:107], v[162:165], v[202:205], v[104:107]
	v_mfma_f32_16x16x32_bf16 v[92:95], v[132:135], v[210:213], v[92:95]
	v_mfma_f32_16x16x32_bf16 v[88:91], v[162:165], v[210:213], v[88:91]
	v_mfma_f32_16x16x32_bf16 v[76:79], v[132:135], v[218:221], v[76:79]
	v_mfma_f32_16x16x32_bf16 v[72:75], v[162:165], v[218:221], v[72:75]
	v_mfma_f32_16x16x32_bf16 v[116:119], v[174:177], v[190:193], v[116:119]
	v_mfma_f32_16x16x32_bf16 v[112:115], v[182:185], v[190:193], v[112:115]
	v_mfma_f32_16x16x32_bf16 v[100:103], v[174:177], v[198:201], v[100:103]
	v_mfma_f32_16x16x32_bf16 v[96:99], v[182:185], v[198:201], v[96:99]
	v_mfma_f32_16x16x32_bf16 v[84:87], v[174:177], v[206:209], v[84:87]
	v_mfma_f32_16x16x32_bf16 v[80:83], v[182:185], v[206:209], v[80:83]
	v_mfma_f32_16x16x32_bf16 v[68:71], v[174:177], v[214:217], v[68:71]
	v_mfma_f32_16x16x32_bf16 v[64:67], v[182:185], v[214:217], v[64:67]
	v_mfma_f32_16x16x32_bf16 v[116:119], v[178:181], v[194:197], v[116:119]
	v_mfma_f32_16x16x32_bf16 v[112:115], v[186:189], v[194:197], v[112:115]
	v_mfma_f32_16x16x32_bf16 v[100:103], v[178:181], v[202:205], v[100:103]
	v_mfma_f32_16x16x32_bf16 v[96:99], v[186:189], v[202:205], v[96:99]
	v_mfma_f32_16x16x32_bf16 v[84:87], v[178:181], v[210:213], v[84:87]
	v_mfma_f32_16x16x32_bf16 v[80:83], v[186:189], v[210:213], v[80:83]
	v_mfma_f32_16x16x32_bf16 v[68:71], v[178:181], v[218:221], v[68:71]
	v_mfma_f32_16x16x32_bf16 v[64:67], v[186:189], v[218:221], v[64:67]
	s_setprio 0
	s_barrier
; #define PG8_STAGE(bufoff, gbase, voff) do { _Pragma("unroll") for (int _i = 0; _i < 2; ++_i) \
;         __builtin_amdgcn_global_load_lds((const unsigned*)((const char*)(gbase) + (voff)[_i]), (PG8_LAS unsigned*)(lds + (bufoff) + ldsw + _i * 8192), 16, 0, 0); } while (0)
; #define PG8_LDA(dst, b, h) do { _Pragma("unroll") for (int m = 0; m < 4; ++m) _Pragma("unroll") for (int k = 0; k < 2; ++k) dst[m][k] = *(const PG8_LAS bf16x8*)(lds + PG8_SA(b, h) + aoff + m * 2048 + k * 1024); } while (0)
; #define PG8_MMA(ai, bj, At, Bt) do { __builtin_amdgcn_s_setprio(1); _Pragma("unroll") for (int m = 0; m < 4; ++m) _Pragma("unroll") for (int n = 0; n < 2; ++n) _Pragma("unroll") for (int k = 0; k < 2; ++k) \
;         acc[ai][bj][m][n] = __builtin_amdgcn_mfma_f32_16x16x32_bf16(Bt[n][k], At[m][k], acc[ai][bj][m][n], 0, 0, 0); __builtin_amdgcn_s_setprio(0); } while (0)
; #define PG8_WAIT_V(n) asm volatile("s_waitcnt vmcnt(" #n ")" ::: "memory")
; #define PG8_WAIT_L(n) asm volatile("s_waitcnt lgkmcnt(" #n ")" ::: "memory")
; #define PG8_BAR __builtin_amdgcn_s_barrier()
; #define PG8_SCHED __builtin_amdgcn_sched_barrier(0)
; template <class Epi, class Sched, bool ALIGN_EPI = false, bool SP2 = false>
; __device__ __forceinline__ void gemm_phase(PG8_LAS unsigned char* lds, const Gemm g, const Sched& S, const Epi& E, int wid_in) {
;     ...
;         for (int t = 0; t < nt; t += 2) {
;     ...
;             PG8_LDA(At, 1, 1); PG8_STAGE(PG8_SB(1, 0), b3, voffB); PG8_STAGE(PG8_SB(1, 1), b3 + hstep, voffB); PG8_STAGE(PG8_SA(1, 0), a3, voffA);
;             PG8_WAIT_V(8); PG8_WAIT_L(0); PG8_BAR; PG8_MMA(1, 0, At, B0); PG8_MMA(1, 1, At, B1); PG8_BAR; PG8_SCHED;
;     ...
;         if constexpr (ALIGN_EPI) { if (wr == 0) PG8_BAR; }
	s_add_i32 s90, s95, s12
	v_lshl_add_u64 v[166:167], v[166:167], 0, s[74:75]
	s_mov_b32 m0, s90
	ds_read_b128 v[190:193], v173 offset:49152
	ds_read_b128 v[194:197], v173 offset:50176
	ds_read_b128 v[198:201], v173 offset:51200
	ds_read_b128 v[202:205], v173 offset:52224
	ds_read_b128 v[206:209], v173 offset:53248
	ds_read_b128 v[210:213], v173 offset:54272
	ds_read_b128 v[214:217], v173 offset:55296
	ds_read_b128 v[218:221], v173 offset:56320
	global_load_lds_dwordx4 v[166:167], off
	s_add_i32 m0, s90, 0x2000
	s_add_u32 s88, s88, 0x40080
	v_lshl_add_u64 v[166:167], v[222:223], 0, s[74:75]
	s_addc_u32 s89, s89, 0
	s_add_i32 s90, vcc_lo, s12
	global_load_lds_dwordx4 v[166:167], off
	v_lshl_add_u64 v[166:167], s[88:89], 0, v[138:139]
	s_mov_b32 m0, s90
	s_nop 0
	global_load_lds_dwordx4 v[166:167], off
	v_lshl_add_u64 v[166:167], s[88:89], 0, v[142:143]
	s_add_i32 m0, s90, 0x2000
	s_nop 0
	global_load_lds_dwordx4 v[166:167], off
	v_lshl_add_u64 v[166:167], v[224:225], 0, s[74:75]
	s_mov_b32 m0, s64
	s_nop 0
	global_load_lds_dwordx4 v[166:167], off
	v_lshl_add_u64 v[166:167], v[226:227], 0, s[74:75]
	s_mov_b32 m0, s65
	s_nop 0
	global_load_lds_dwordx4 v[166:167], off
	s_waitcnt vmcnt(8)
	s_waitcnt lgkmcnt(0)
	s_barrier
	s_setprio 1
	v_mfma_f32_16x16x32_bf16 v[60:63], v[128:131], v[190:193], v[60:63]
	v_mfma_f32_16x16x32_bf16 v[56:59], v[158:161], v[190:193], v[56:59]
	v_mfma_f32_16x16x32_bf16 v[44:47], v[128:131], v[198:201], v[44:47]
	v_mfma_f32_16x16x32_bf16 v[40:43], v[158:161], v[198:201], v[40:43]
	v_mfma_f32_16x16x32_bf16 v[28:31], v[128:131], v[206:209], v[28:31]
	v_mfma_f32_16x16x32_bf16 v[24:27], v[158:161], v[206:209], v[24:27]
	v_mfma_f32_16x16x32_bf16 v[12:15], v[128:131], v[214:217], v[12:15]
	v_mfma_f32_16x16x32_bf16 v[8:11], v[158:161], v[214:217], v[8:11]
	v_mfma_f32_16x16x32_bf16 v[60:63], v[132:135], v[194:197], v[60:63]
	v_mfma_f32_16x16x32_bf16 v[56:59], v[162:165], v[194:197], v[56:59]
	v_mfma_f32_16x16x32_bf16 v[44:47], v[132:135], v[202:205], v[44:47]
	v_mfma_f32_16x16x32_bf16 v[40:43], v[162:165], v[202:205], v[40:43]
	v_mfma_f32_16x16x32_bf16 v[28:31], v[132:135], v[210:213], v[28:31]
	v_mfma_f32_16x16x32_bf16 v[24:27], v[162:165], v[210:213], v[24:27]
	v_mfma_f32_16x16x32_bf16 v[12:15], v[132:135], v[218:221], v[12:15]
	v_mfma_f32_16x16x32_bf16 v[8:11], v[162:165], v[218:221], v[8:11]
	v_mfma_f32_16x16x32_bf16 v[52:55], v[174:177], v[190:193], v[52:55]
	v_mfma_f32_16x16x32_bf16 v[48:51], v[182:185], v[190:193], v[48:51]
	v_mfma_f32_16x16x32_bf16 v[36:39], v[174:177], v[198:201], v[36:39]
	v_mfma_f32_16x16x32_bf16 v[32:35], v[182:185], v[198:201], v[32:35]
	v_mfma_f32_16x16x32_bf16 v[20:23], v[174:177], v[206:209], v[20:23]
	v_mfma_f32_16x16x32_bf16 v[16:19], v[182:185], v[206:209], v[16:19]
	v_mfma_f32_16x16x32_bf16 v[4:7], v[174:177], v[214:217], v[4:7]
	v_mfma_f32_16x16x32_bf16 v[0:3], v[182:185], v[214:217], v[0:3]
	v_mfma_f32_16x16x32_bf16 v[52:55], v[178:181], v[194:197], v[52:55]
	v_mfma_f32_16x16x32_bf16 v[48:51], v[186:189], v[194:197], v[48:51]
	v_mfma_f32_16x16x32_bf16 v[36:39], v[178:181], v[202:205], v[36:39]
	v_mfma_f32_16x16x32_bf16 v[32:35], v[186:189], v[202:205], v[32:35]
	v_mfma_f32_16x16x32_bf16 v[20:23], v[178:181], v[210:213], v[20:23]
	v_mfma_f32_16x16x32_bf16 v[16:19], v[186:189], v[210:213], v[16:19]
	v_mfma_f32_16x16x32_bf16 v[4:7], v[178:181], v[218:221], v[4:7]
	v_mfma_f32_16x16x32_bf16 v[0:3], v[186:189], v[218:221], v[0:3]
	s_setprio 0
	s_barrier
	s_add_i32 s94, s94, 2
	s_add_u32 s68, s68, 0x100
	s_addc_u32 s69, s69, 0
	s_add_u32 s92, s92, 0x100
	s_addc_u32 s93, s93, 0
	s_cmp_gt_u32 s94, 13
	s_cbranch_scc0 .LBB0_227
	s_and_b64 vcc, exec, s[76:77]
	s_cbranch_vccz .LBB0_230
	s_barrier

; template <int ROT, class Epi0, class Epi1, class Late, class Post0>
; __device__ __forceinline__ void gemm_phase_pair(PG8_LAS unsigned char* lds, const Gemm g0, const Gemm g1, const Unit u, const Epi0& E0, const Epi1& E1, int wid_in, const Late& late, const Post0& post0) {
;     ...
;     for (int t = 0; t < t_late; t += 2) {
;         const char* a1 = cA + PG8_KT(t + 1); const char* a2 = cA + PG8_KT(t + 2); const char* b2 = cB + PG8_KT(t + 2); const char* a3 = cA + PG8_KT(t + 3); const char* b3 = cB + PG8_KT(t + 3);
;         PG8_PAIR_ITER(a1 + hs0, vA0, a2, b2, a3, b3, vA0, vB0, hs0);
;     }
.LBB0_847:
	s_nop 0
	ds_read_b128 v[144:147], v141
	ds_read_b128 v[148:151], v141 offset:1024
	ds_read_b128 v[152:155], v141 offset:2048
	ds_read_b128 v[156:159], v141 offset:3072
	ds_read_b128 v[160:163], v140
	ds_read_b128 v[164:167], v140 offset:1024
	ds_read_b128 v[168:171], v140 offset:2048
	ds_read_b128 v[172:175], v140 offset:3072
	s_add_u32 s62, s38, s18
	s_addc_u32 s63, s39, s19
	v_lshl_add_u64 v[208:209], s[62:63], 0, v[130:131]
	s_mov_b32 m0, s51
	v_lshl_add_u64 v[210:211], v[208:209], 0, s[4:5]
	v_mov_b32_e32 v129, v131
	ds_read_b128 v[176:179], v137
	ds_read_b128 v[180:183], v137 offset:1024
	ds_read_b128 v[184:187], v137 offset:2048
	ds_read_b128 v[188:191], v137 offset:3072
	ds_read_b128 v[192:195], v137 offset:4096
	ds_read_b128 v[196:199], v137 offset:5120
	ds_read_b128 v[200:203], v137 offset:6144
	ds_read_b128 v[204:207], v137 offset:7168
	global_load_lds_dwordx4 v[210:211], off
	v_lshl_add_u64 v[210:211], s[62:63], 0, v[128:129]
	v_lshl_add_u64 v[212:213], v[210:211], 0, s[4:5]
	s_mov_b32 m0, s50
	s_nop 0
	global_load_lds_dwordx4 v[212:213], off
	s_waitcnt vmcnt(8)
	s_waitcnt lgkmcnt(0)
	s_barrier
	s_setprio 1
	v_mfma_f32_16x16x32_bf16 v[124:127], v[144:147], v[176:179], v[124:127]
	v_mfma_f32_16x16x32_bf16 v[120:123], v[152:155], v[176:179], v[120:123]
	v_mfma_f32_16x16x32_bf16 v[116:119], v[144:147], v[184:187], v[116:119]
	v_mfma_f32_16x16x32_bf16 v[112:115], v[152:155], v[184:187], v[112:115]
	v_mfma_f32_16x16x32_bf16 v[108:111], v[144:147], v[192:195], v[108:111]
	v_mfma_f32_16x16x32_bf16 v[104:107], v[152:155], v[192:195], v[104:107]
	v_mfma_f32_16x16x32_bf16 v[100:103], v[144:147], v[200:203], v[100:103]
	v_mfma_f32_16x16x32_bf16 v[96:99], v[152:155], v[200:203], v[96:99]
	v_mfma_f32_16x16x32_bf16 v[124:127], v[148:151], v[180:183], v[124:127]
	v_mfma_f32_16x16x32_bf16 v[120:123], v[156:159], v[180:183], v[120:123]
	v_mfma_f32_16x16x32_bf16 v[116:119], v[148:151], v[188:191], v[116:119]
	v_mfma_f32_16x16x32_bf16 v[112:115], v[156:159], v[188:191], v[112:115]
	v_mfma_f32_16x16x32_bf16 v[108:111], v[148:151], v[196:199], v[108:111]
	v_mfma_f32_16x16x32_bf16 v[104:107], v[156:159], v[196:199], v[104:107]
	v_mfma_f32_16x16x32_bf16 v[100:103], v[148:151], v[204:207], v[100:103]
	v_mfma_f32_16x16x32_bf16 v[96:99], v[156:159], v[204:207], v[96:99]
	v_mfma_f32_16x16x32_bf16 v[92:95], v[160:163], v[176:179], v[92:95]
	v_mfma_f32_16x16x32_bf16 v[88:91], v[168:171], v[176:179], v[88:91]
	v_mfma_f32_16x16x32_bf16 v[84:87], v[160:163], v[184:187], v[84:87]
	v_mfma_f32_16x16x32_bf16 v[80:83], v[168:171], v[184:187], v[80:83]
	v_mfma_f32_16x16x32_bf16 v[76:79], v[160:163], v[192:195], v[76:79]
	v_mfma_f32_16x16x32_bf16 v[72:75], v[168:171], v[192:195], v[72:75]
	v_mfma_f32_16x16x32_bf16 v[68:71], v[160:163], v[200:203], v[68:71]
	v_mfma_f32_16x16x32_bf16 v[64:67], v[168:171], v[200:203], v[64:67]
	v_mfma_f32_16x16x32_bf16 v[92:95], v[164:167], v[180:183], v[92:95]
	v_mfma_f32_16x16x32_bf16 v[88:91], v[172:175], v[180:183], v[88:91]
	v_mfma_f32_16x16x32_bf16 v[84:87], v[164:167], v[188:191], v[84:87]
	v_mfma_f32_16x16x32_bf16 v[80:83], v[172:175], v[188:191], v[80:83]
	v_mfma_f32_16x16x32_bf16 v[76:79], v[164:167], v[196:199], v[76:79]
	v_mfma_f32_16x16x32_bf16 v[72:75], v[172:175], v[196:199], v[72:75]
	v_mfma_f32_16x16x32_bf16 v[68:71], v[164:167], v[204:207], v[68:71]
	v_mfma_f32_16x16x32_bf16 v[64:67], v[172:175], v[204:207], v[64:67]
	s_setprio 0
	s_barrier
	s_add_u32 s62, s38, s20
	v_mov_b32_e32 v133, v131
	s_addc_u32 s63, s39, s21
	v_lshl_add_u64 v[212:213], s[62:63], 0, v[132:133]
	s_mov_b32 m0, s49
	v_lshl_add_u64 v[214:215], v[212:213], 0, s[6:7]
	v_mov_b32_e32 v135, v131
	ds_read_b128 v[176:179], v137 offset:16384
	ds_read_b128 v[180:183], v137 offset:17408
	ds_read_b128 v[184:187], v137 offset:18432
	ds_read_b128 v[188:191], v137 offset:19456
	ds_read_b128 v[192:195], v137 offset:20480
	ds_read_b128 v[196:199], v137 offset:21504
	ds_read_b128 v[200:203], v137 offset:22528
	ds_read_b128 v[204:207], v137 offset:23552
	global_load_lds_dwordx4 v[214:215], off
	v_lshl_add_u64 v[214:215], s[62:63], 0, v[134:135]
	v_lshl_add_u64 v[216:217], v[214:215], 0, s[6:7]
	s_mov_b32 m0, s47
	s_nop 0
	global_load_lds_dwordx4 v[216:217], off
	v_lshl_add_u64 v[216:217], v[212:213], 0, s[10:11]
	s_mov_b32 m0, s48
	s_nop 0
	global_load_lds_dwordx4 v[216:217], off
	v_lshl_add_u64 v[216:217], v[214:215], 0, s[10:11]
	s_mov_b32 m0, s46
	s_nop 0
	global_load_lds_dwordx4 v[216:217], off
	v_lshl_add_u64 v[216:217], v[208:209], 0, s[24:25]
	s_mov_b32 m0, s40
	s_nop 0
	global_load_lds_dwordx4 v[216:217], off
	v_lshl_add_u64 v[216:217], v[210:211], 0, s[24:25]
	s_mov_b32 m0, s45
	s_nop 0
	global_load_lds_dwordx4 v[216:217], off
	s_waitcnt vmcnt(8)
	s_waitcnt lgkmcnt(0)
	s_barrier
	s_setprio 1
	v_mfma_f32_16x16x32_bf16 v[60:63], v[144:147], v[176:179], v[60:63]
	v_mfma_f32_16x16x32_bf16 v[56:59], v[152:155], v[176:179], v[56:59]
	v_mfma_f32_16x16x32_bf16 v[52:55], v[144:147], v[184:187], v[52:55]
	v_mfma_f32_16x16x32_bf16 v[48:51], v[152:155], v[184:187], v[48:51]
	v_mfma_f32_16x16x32_bf16 v[44:47], v[144:147], v[192:195], v[44:47]
	v_mfma_f32_16x16x32_bf16 v[40:43], v[152:155], v[192:195], v[40:43]
	v_mfma_f32_16x16x32_bf16 v[36:39], v[144:147], v[200:203], v[36:39]
	v_mfma_f32_16x16x32_bf16 v[32:35], v[152:155], v[200:203], v[32:35]
	v_mfma_f32_16x16x32_bf16 v[60:63], v[148:151], v[180:183], v[60:63]
	v_mfma_f32_16x16x32_bf16 v[56:59], v[156:159], v[180:183], v[56:59]
	v_mfma_f32_16x16x32_bf16 v[52:55], v[148:151], v[188:191], v[52:55]
	v_mfma_f32_16x16x32_bf16 v[48:51], v[156:159], v[188:191], v[48:51]
	v_mfma_f32_16x16x32_bf16 v[44:47], v[148:151], v[196:199], v[44:47]
	v_mfma_f32_16x16x32_bf16 v[40:43], v[156:159], v[196:199], v[40:43]
	v_mfma_f32_16x16x32_bf16 v[36:39], v[148:151], v[204:207], v[36:39]
	v_mfma_f32_16x16x32_bf16 v[32:35], v[156:159], v[204:207], v[32:35]
	v_mfma_f32_16x16x32_bf16 v[28:31], v[160:163], v[176:179], v[28:31]
	v_mfma_f32_16x16x32_bf16 v[24:27], v[168:171], v[176:179], v[24:27]
	v_mfma_f32_16x16x32_bf16 v[20:23], v[160:163], v[184:187], v[20:23]
	v_mfma_f32_16x16x32_bf16 v[16:19], v[168:171], v[184:187], v[16:19]
	v_mfma_f32_16x16x32_bf16 v[12:15], v[160:163], v[192:195], v[12:15]
	v_mfma_f32_16x16x32_bf16 v[8:11], v[168:171], v[192:195], v[8:11]
	v_mfma_f32_16x16x32_bf16 v[4:7], v[160:163], v[200:203], v[4:7]
	v_mfma_f32_16x16x32_bf16 v[0:3], v[168:171], v[200:203], v[0:3]
	v_mfma_f32_16x16x32_bf16 v[28:31], v[164:167], v[180:183], v[28:31]
	v_mfma_f32_16x16x32_bf16 v[24:27], v[172:175], v[180:183], v[24:27]
	v_mfma_f32_16x16x32_bf16 v[20:23], v[164:167], v[188:191], v[20:23]
	v_mfma_f32_16x16x32_bf16 v[16:19], v[172:175], v[188:191], v[16:19]
	v_mfma_f32_16x16x32_bf16 v[12:15], v[164:167], v[196:199], v[12:15]
	v_mfma_f32_16x16x32_bf16 v[8:11], v[172:175], v[196:199], v[8:11]
	v_mfma_f32_16x16x32_bf16 v[4:7], v[164:167], v[204:207], v[4:7]
	v_mfma_f32_16x16x32_bf16 v[0:3], v[172:175], v[204:207], v[0:3]
	s_setprio 0
	s_barrier
	ds_read_b128 v[144:147], v139
	ds_read_b128 v[148:151], v139 offset:1024
	ds_read_b128 v[152:155], v139 offset:2048
	ds_read_b128 v[156:159], v139 offset:3072
	ds_read_b128 v[160:163], v138
	ds_read_b128 v[164:167], v138 offset:1024
	ds_read_b128 v[168:171], v138 offset:2048
	ds_read_b128 v[172:175], v138 offset:3072
	s_mov_b32 m0, s34
	v_lshl_add_u64 v[216:217], v[208:209], 0, s[26:27]
	ds_read_b128 v[176:179], v137 offset:32768
	ds_read_b128 v[180:183], v137 offset:33792
	ds_read_b128 v[184:187], v137 offset:34816
	ds_read_b128 v[188:191], v137 offset:35840
	ds_read_b128 v[192:195], v137 offset:36864
	ds_read_b128 v[196:199], v137 offset:37888
	ds_read_b128 v[200:203], v137 offset:38912
	ds_read_b128 v[204:207], v137 offset:39936
	global_load_lds_dwordx4 v[216:217], off
	v_lshl_add_u64 v[216:217], v[210:211], 0, s[26:27]
	s_mov_b32 m0, s35
	s_nop 0
	global_load_lds_dwordx4 v[216:217], off
	s_waitcnt vmcnt(8)
	s_waitcnt lgkmcnt(0)
	s_barrier
	s_setprio 1
	v_mfma_f32_16x16x32_bf16 v[124:127], v[144:147], v[176:179], v[124:127]
	v_mfma_f32_16x16x32_bf16 v[120:123], v[152:155], v[176:179], v[120:123]
	v_mfma_f32_16x16x32_bf16 v[116:119], v[144:147], v[184:187], v[116:119]
	v_mfma_f32_16x16x32_bf16 v[112:115], v[152:155], v[184:187], v[112:115]
	v_mfma_f32_16x16x32_bf16 v[108:111], v[144:147], v[192:195], v[108:111]
	v_mfma_f32_16x16x32_bf16 v[104:107], v[152:155], v[192:195], v[104:107]
	v_mfma_f32_16x16x32_bf16 v[100:103], v[144:147], v[200:203], v[100:103]
	v_mfma_f32_16x16x32_bf16 v[96:99], v[152:155], v[200:203], v[96:99]
	v_mfma_f32_16x16x32_bf16 v[124:127], v[148:151], v[180:183], v[124:127]
	v_mfma_f32_16x16x32_bf16 v[120:123], v[156:159], v[180:183], v[120:123]
	v_mfma_f32_16x16x32_bf16 v[116:119], v[148:151], v[188:191], v[116:119]
	v_mfma_f32_16x16x32_bf16 v[112:115], v[156:159], v[188:191], v[112:115]
	v_mfma_f32_16x16x32_bf16 v[108:111], v[148:151], v[196:199], v[108:111]
	v_mfma_f32_16x16x32_bf16 v[104:107], v[156:159], v[196:199], v[104:107]
	v_mfma_f32_16x16x32_bf16 v[100:103], v[148:151], v[204:207], v[100:103]
	v_mfma_f32_16x16x32_bf16 v[96:99], v[156:159], v[204:207], v[96:99]
	v_mfma_f32_16x16x32_bf16 v[92:95], v[160:163], v[176:179], v[92:95]
	v_mfma_f32_16x16x32_bf16 v[88:91], v[168:171], v[176:179], v[88:91]
	v_mfma_f32_16x16x32_bf16 v[84:87], v[160:163], v[184:187], v[84:87]
	v_mfma_f32_16x16x32_bf16 v[80:83], v[168:171], v[184:187], v[80:83]
	v_mfma_f32_16x16x32_bf16 v[76:79], v[160:163], v[192:195], v[76:79]
	v_mfma_f32_16x16x32_bf16 v[72:75], v[168:171], v[192:195], v[72:75]
	v_mfma_f32_16x16x32_bf16 v[68:71], v[160:163], v[200:203], v[68:71]
	v_mfma_f32_16x16x32_bf16 v[64:67], v[168:171], v[200:203], v[64:67]
	v_mfma_f32_16x16x32_bf16 v[92:95], v[164:167], v[180:183], v[92:95]
	v_mfma_f32_16x16x32_bf16 v[88:91], v[172:175], v[180:183], v[88:91]
	v_mfma_f32_16x16x32_bf16 v[84:87], v[164:167], v[188:191], v[84:87]
	v_mfma_f32_16x16x32_bf16 v[80:83], v[172:175], v[188:191], v[80:83]
	v_mfma_f32_16x16x32_bf16 v[76:79], v[164:167], v[196:199], v[76:79]
	v_mfma_f32_16x16x32_bf16 v[72:75], v[172:175], v[196:199], v[72:75]
	v_mfma_f32_16x16x32_bf16 v[68:71], v[164:167], v[204:207], v[68:71]
	v_mfma_f32_16x16x32_bf16 v[64:67], v[172:175], v[204:207], v[64:67]
	s_setprio 0
	s_barrier
; #define PG8_BAR __builtin_amdgcn_s_barrier()
; template <int ROT, class Epi0, class Epi1, class Late, class Post0>
; __device__ __forceinline__ void gemm_phase_pair(PG8_LAS unsigned char* lds, const Gemm g0, const Gemm g1, const Unit u, const Epi0& E0, const Epi1& E1, int wid_in, const Late& late, const Post0& post0) {
;     ...
;     for (int t = 0; t < t_late; t += 2) {
;     ...
;         if (wr == 0) PG8_BAR;
	s_mov_b32 m0, s44
	v_lshl_add_u64 v[216:217], v[212:213], 0, s[28:29]
	ds_read_b128 v[176:179], v137 offset:49152
	ds_read_b128 v[180:183], v137 offset:50176
	ds_read_b128 v[184:187], v137 offset:51200
	ds_read_b128 v[188:191], v137 offset:52224
	ds_read_b128 v[192:195], v137 offset:53248
	ds_read_b128 v[196:199], v137 offset:54272
	ds_read_b128 v[200:203], v137 offset:55296
	ds_read_b128 v[204:207], v137 offset:56320
	global_load_lds_dwordx4 v[216:217], off
	v_lshl_add_u64 v[216:217], v[214:215], 0, s[28:29]
	s_mov_b32 m0, s42
	v_lshl_add_u64 v[212:213], v[212:213], 0, s[30:31]
	global_load_lds_dwordx4 v[216:217], off
	s_mov_b32 m0, s43
	v_lshl_add_u64 v[208:209], v[208:209], 0, s[36:37]
	global_load_lds_dwordx4 v[212:213], off
	v_lshl_add_u64 v[212:213], v[214:215], 0, s[30:31]
	s_mov_b32 m0, s41
	s_nop 0
	global_load_lds_dwordx4 v[212:213], off
	s_mov_b32 m0, s13
	s_nop 0
	global_load_lds_dwordx4 v[208:209], off
	v_lshl_add_u64 v[208:209], v[210:211], 0, s[36:37]
	s_mov_b32 m0, s33
	s_nop 0
	global_load_lds_dwordx4 v[208:209], off
	s_waitcnt vmcnt(8)
	s_waitcnt lgkmcnt(0)
	s_barrier
	s_setprio 1
	v_mfma_f32_16x16x32_bf16 v[60:63], v[144:147], v[176:179], v[60:63]
	v_mfma_f32_16x16x32_bf16 v[56:59], v[152:155], v[176:179], v[56:59]
	v_mfma_f32_16x16x32_bf16 v[52:55], v[144:147], v[184:187], v[52:55]
	v_mfma_f32_16x16x32_bf16 v[48:51], v[152:155], v[184:187], v[48:51]
	v_mfma_f32_16x16x32_bf16 v[44:47], v[144:147], v[192:195], v[44:47]
	v_mfma_f32_16x16x32_bf16 v[40:43], v[152:155], v[192:195], v[40:43]
	v_mfma_f32_16x16x32_bf16 v[36:39], v[144:147], v[200:203], v[36:39]
	v_mfma_f32_16x16x32_bf16 v[32:35], v[152:155], v[200:203], v[32:35]
	v_mfma_f32_16x16x32_bf16 v[60:63], v[148:151], v[180:183], v[60:63]
	v_mfma_f32_16x16x32_bf16 v[56:59], v[156:159], v[180:183], v[56:59]
	v_mfma_f32_16x16x32_bf16 v[52:55], v[148:151], v[188:191], v[52:55]
	v_mfma_f32_16x16x32_bf16 v[48:51], v[156:159], v[188:191], v[48:51]
	v_mfma_f32_16x16x32_bf16 v[44:47], v[148:151], v[196:199], v[44:47]
	v_mfma_f32_16x16x32_bf16 v[40:43], v[156:159], v[196:199], v[40:43]
	v_mfma_f32_16x16x32_bf16 v[36:39], v[148:151], v[204:207], v[36:39]
	v_mfma_f32_16x16x32_bf16 v[32:35], v[156:159], v[204:207], v[32:35]
	v_mfma_f32_16x16x32_bf16 v[28:31], v[160:163], v[176:179], v[28:31]
	v_mfma_f32_16x16x32_bf16 v[24:27], v[168:171], v[176:179], v[24:27]
	v_mfma_f32_16x16x32_bf16 v[20:23], v[160:163], v[184:187], v[20:23]
	v_mfma_f32_16x16x32_bf16 v[16:19], v[168:171], v[184:187], v[16:19]
	v_mfma_f32_16x16x32_bf16 v[12:15], v[160:163], v[192:195], v[12:15]
	v_mfma_f32_16x16x32_bf16 v[8:11], v[168:171], v[192:195], v[8:11]
	v_mfma_f32_16x16x32_bf16 v[4:7], v[160:163], v[200:203], v[4:7]
	v_mfma_f32_16x16x32_bf16 v[0:3], v[168:171], v[200:203], v[0:3]
	v_mfma_f32_16x16x32_bf16 v[28:31], v[164:167], v[180:183], v[28:31]
	v_mfma_f32_16x16x32_bf16 v[24:27], v[172:175], v[180:183], v[24:27]
	v_mfma_f32_16x16x32_bf16 v[20:23], v[164:167], v[188:191], v[20:23]
	v_mfma_f32_16x16x32_bf16 v[16:19], v[172:175], v[188:191], v[16:19]
	v_mfma_f32_16x16x32_bf16 v[12:15], v[164:167], v[196:199], v[12:15]
	v_mfma_f32_16x16x32_bf16 v[8:11], v[172:175], v[196:199], v[8:11]
	v_mfma_f32_16x16x32_bf16 v[4:7], v[164:167], v[204:207], v[4:7]
	v_mfma_f32_16x16x32_bf16 v[0:3], v[172:175], v[204:207], v[0:3]
	s_setprio 0
	s_barrier
	s_add_i32 s53, s53, 2
	s_add_u32 s38, s38, 0x100
	s_addc_u32 s39, s39, 0
	s_cmp_gt_u32 s53, 11
	s_cbranch_scc0 .LBB0_847
	s_cmpk_lt_u32 s71, 0x100
	s_cselect_b64 s[4:5], -1, 0
	s_and_b64 vcc, exec, s[4:5]
	s_cbranch_vccz .LBB0_850
	s_barrier

; template <int ROT, class Epi0, class Epi1, class Late, class Post0>
; __device__ __forceinline__ void gemm_phase_pair(PG8_LAS unsigned char* lds, const Gemm g0, const Gemm g1, const Unit u, const Epi0& E0, const Epi1& E1, int wid_in, const Late& late, const Post0& post0) {
;     ...
;     for (int t = t_late; t < nt0 - 2; t += 2) {
;         if constexpr (Epi0::HAS_MID) { if (t == nt0 / 2) E0.mid(acc, u, wr, wc, fr, fq); }
;         const char* a1 = cA + PG8_KT(t + 1); const char* a2 = cA + PG8_KT(t + 2); const char* b2 = cB + PG8_KT(t + 2); const char* a3 = cA + PG8_KT(t + 3); const char* b3 = cB + PG8_KT(t + 3);
;         PG8_PAIR_ITER(a1 + hs0, vA0, a2, b2, a3, b3, vA0, vB0, hs0);
.LBB0_874:
	s_add_i32 s63, s18, 0xf80
	ds_read_b128 v[146:149], v141
	ds_read_b128 v[150:153], v141 offset:1024
	ds_read_b128 v[154:157], v141 offset:2048
	ds_read_b128 v[158:161], v141 offset:3072
	ds_read_b128 v[162:165], v140
	ds_read_b128 v[166:169], v140 offset:1024
	ds_read_b128 v[170:173], v140 offset:2048
	ds_read_b128 v[174:177], v140 offset:3072
	s_and_b32 s63, s63, 0xf80
	s_add_u32 s63, s16, s63
	s_addc_u32 s65, s17, 0
	s_add_u32 s64, s63, 0x80000
	s_mov_b32 m0, s51
	s_addc_u32 s65, s65, 0
	ds_read_b128 v[178:181], v137
	ds_read_b128 v[182:185], v137 offset:1024
	ds_read_b128 v[186:189], v137 offset:2048
	ds_read_b128 v[190:193], v137 offset:3072
	ds_read_b128 v[194:197], v137 offset:4096
	ds_read_b128 v[198:201], v137 offset:5120
	ds_read_b128 v[202:205], v137 offset:6144
	ds_read_b128 v[206:209], v137 offset:7168
	global_load_lds_dwordx4 v130, s[64:65]
	s_mov_b32 m0, s50
	v_mov_b32_e32 v129, v131
	global_load_lds_dwordx4 v128, s[64:65]
	s_waitcnt vmcnt(8)
	s_waitcnt lgkmcnt(0)
	s_barrier
	s_setprio 1
	v_mfma_f32_16x16x32_bf16 v[124:127], v[146:149], v[178:181], v[124:127]
	v_mfma_f32_16x16x32_bf16 v[120:123], v[154:157], v[178:181], v[120:123]
	v_mfma_f32_16x16x32_bf16 v[116:119], v[146:149], v[186:189], v[116:119]
	v_mfma_f32_16x16x32_bf16 v[112:115], v[154:157], v[186:189], v[112:115]
	v_mfma_f32_16x16x32_bf16 v[108:111], v[146:149], v[194:197], v[108:111]
	v_mfma_f32_16x16x32_bf16 v[104:107], v[154:157], v[194:197], v[104:107]
	v_mfma_f32_16x16x32_bf16 v[100:103], v[146:149], v[202:205], v[100:103]
	v_mfma_f32_16x16x32_bf16 v[96:99], v[154:157], v[202:205], v[96:99]
	v_mfma_f32_16x16x32_bf16 v[124:127], v[150:153], v[182:185], v[124:127]
	v_mfma_f32_16x16x32_bf16 v[120:123], v[158:161], v[182:185], v[120:123]
	v_mfma_f32_16x16x32_bf16 v[116:119], v[150:153], v[190:193], v[116:119]
	v_mfma_f32_16x16x32_bf16 v[112:115], v[158:161], v[190:193], v[112:115]
	v_mfma_f32_16x16x32_bf16 v[108:111], v[150:153], v[198:201], v[108:111]
	v_mfma_f32_16x16x32_bf16 v[104:107], v[158:161], v[198:201], v[104:107]
	v_mfma_f32_16x16x32_bf16 v[100:103], v[150:153], v[206:209], v[100:103]
	v_mfma_f32_16x16x32_bf16 v[96:99], v[158:161], v[206:209], v[96:99]
	v_mfma_f32_16x16x32_bf16 v[92:95], v[162:165], v[178:181], v[92:95]
	v_mfma_f32_16x16x32_bf16 v[88:91], v[170:173], v[178:181], v[88:91]
	v_mfma_f32_16x16x32_bf16 v[84:87], v[162:165], v[186:189], v[84:87]
	v_mfma_f32_16x16x32_bf16 v[80:83], v[170:173], v[186:189], v[80:83]
	v_mfma_f32_16x16x32_bf16 v[76:79], v[162:165], v[194:197], v[76:79]
	v_mfma_f32_16x16x32_bf16 v[72:75], v[170:173], v[194:197], v[72:75]
	v_mfma_f32_16x16x32_bf16 v[68:71], v[162:165], v[202:205], v[68:71]
	v_mfma_f32_16x16x32_bf16 v[64:67], v[170:173], v[202:205], v[64:67]
	v_mfma_f32_16x16x32_bf16 v[92:95], v[166:169], v[182:185], v[92:95]
	v_mfma_f32_16x16x32_bf16 v[88:91], v[174:177], v[182:185], v[88:91]
	v_mfma_f32_16x16x32_bf16 v[84:87], v[166:169], v[190:193], v[84:87]
	v_mfma_f32_16x16x32_bf16 v[80:83], v[174:177], v[190:193], v[80:83]
	v_mfma_f32_16x16x32_bf16 v[76:79], v[166:169], v[198:201], v[76:79]
	v_mfma_f32_16x16x32_bf16 v[72:75], v[174:177], v[198:201], v[72:75]
	v_mfma_f32_16x16x32_bf16 v[68:71], v[166:169], v[206:209], v[68:71]
	v_mfma_f32_16x16x32_bf16 v[64:67], v[174:177], v[206:209], v[64:67]
	s_setprio 0
	s_barrier
	s_add_u32 s64, s38, s18
	v_mov_b32_e32 v133, v131
	s_addc_u32 s65, s39, s19
	v_lshl_add_u64 v[210:211], s[64:65], 0, v[132:133]
	s_mov_b32 m0, s49
	v_lshl_add_u64 v[212:213], v[210:211], 0, s[20:21]
	v_mov_b32_e32 v135, v131
	ds_read_b128 v[178:181], v137 offset:16384
	ds_read_b128 v[182:185], v137 offset:17408
	ds_read_b128 v[186:189], v137 offset:18432
	ds_read_b128 v[190:193], v137 offset:19456
	ds_read_b128 v[194:197], v137 offset:20480
	ds_read_b128 v[198:201], v137 offset:21504
	ds_read_b128 v[202:205], v137 offset:22528
	ds_read_b128 v[206:209], v137 offset:23552
	global_load_lds_dwordx4 v[212:213], off
	v_lshl_add_u64 v[212:213], s[64:65], 0, v[134:135]
	v_lshl_add_u64 v[214:215], v[212:213], 0, s[20:21]
	s_mov_b32 m0, s47
	s_add_u32 s64, s53, s18
	global_load_lds_dwordx4 v[214:215], off
	v_lshl_add_u64 v[214:215], v[210:211], 0, s[22:23]
	s_mov_b32 m0, s48
	s_addc_u32 s65, s61, s19
	global_load_lds_dwordx4 v[214:215], off
	v_lshl_add_u64 v[214:215], v[212:213], 0, s[22:23]
	s_mov_b32 m0, s46
	s_nop 0
	global_load_lds_dwordx4 v[214:215], off
	v_lshl_add_u64 v[214:215], s[64:65], 0, v[130:131]
	v_lshl_add_u64 v[216:217], v[214:215], 0, s[24:25]
	s_mov_b32 m0, s40
	s_nop 0
	global_load_lds_dwordx4 v[216:217], off
	v_lshl_add_u64 v[216:217], s[64:65], 0, v[128:129]
	v_lshl_add_u64 v[218:219], v[216:217], 0, s[24:25]
	s_mov_b32 m0, s45
	s_nop 0
	global_load_lds_dwordx4 v[218:219], off
	s_waitcnt vmcnt(8)
	s_waitcnt lgkmcnt(0)
	s_barrier
; template <int ROT, class Epi0, class Epi1, class Late, class Post0>
; __device__ __forceinline__ void gemm_phase_pair(PG8_LAS unsigned char* lds, const Gemm g0, const Gemm g1, const Unit u, const Epi0& E0, const Epi1& E1, int wid_in, const Late& late, const Post0& post0) {
;     ...
;     for (int t = t_late; t < nt0 - 2; t += 2) {
;         if constexpr (Epi0::HAS_MID) { if (t == nt0 / 2) E0.mid(acc, u, wr, wc, fr, fq); }
;         const char* a1 = cA + PG8_KT(t + 1); const char* a2 = cA + PG8_KT(t + 2); const char* b2 = cB + PG8_KT(t + 2); const char* a3 = cA + PG8_KT(t + 3); const char* b3 = cB + PG8_KT(t + 3);
;         PG8_PAIR_ITER(a1 + hs0, vA0, a2, b2, a3, b3, vA0, vB0, hs0);
;     }
	s_setprio 1
	v_mfma_f32_16x16x32_bf16 v[60:63], v[146:149], v[178:181], v[60:63]
	v_mfma_f32_16x16x32_bf16 v[56:59], v[154:157], v[178:181], v[56:59]
	v_mfma_f32_16x16x32_bf16 v[52:55], v[146:149], v[186:189], v[52:55]
	v_mfma_f32_16x16x32_bf16 v[48:51], v[154:157], v[186:189], v[48:51]
	v_mfma_f32_16x16x32_bf16 v[44:47], v[146:149], v[194:197], v[44:47]
	v_mfma_f32_16x16x32_bf16 v[40:43], v[154:157], v[194:197], v[40:43]
	v_mfma_f32_16x16x32_bf16 v[36:39], v[146:149], v[202:205], v[36:39]
	v_mfma_f32_16x16x32_bf16 v[32:35], v[154:157], v[202:205], v[32:35]
	v_mfma_f32_16x16x32_bf16 v[60:63], v[150:153], v[182:185], v[60:63]
	v_mfma_f32_16x16x32_bf16 v[56:59], v[158:161], v[182:185], v[56:59]
	v_mfma_f32_16x16x32_bf16 v[52:55], v[150:153], v[190:193], v[52:55]
	v_mfma_f32_16x16x32_bf16 v[48:51], v[158:161], v[190:193], v[48:51]
	v_mfma_f32_16x16x32_bf16 v[44:47], v[150:153], v[198:201], v[44:47]
	v_mfma_f32_16x16x32_bf16 v[40:43], v[158:161], v[198:201], v[40:43]
	v_mfma_f32_16x16x32_bf16 v[36:39], v[150:153], v[206:209], v[36:39]
	v_mfma_f32_16x16x32_bf16 v[32:35], v[158:161], v[206:209], v[32:35]
	v_mfma_f32_16x16x32_bf16 v[28:31], v[162:165], v[178:181], v[28:31]
	v_mfma_f32_16x16x32_bf16 v[24:27], v[170:173], v[178:181], v[24:27]
	v_mfma_f32_16x16x32_bf16 v[20:23], v[162:165], v[186:189], v[20:23]
	v_mfma_f32_16x16x32_bf16 v[16:19], v[170:173], v[186:189], v[16:19]
	v_mfma_f32_16x16x32_bf16 v[12:15], v[162:165], v[194:197], v[12:15]
	v_mfma_f32_16x16x32_bf16 v[8:11], v[170:173], v[194:197], v[8:11]
	v_mfma_f32_16x16x32_bf16 v[4:7], v[162:165], v[202:205], v[4:7]
	v_mfma_f32_16x16x32_bf16 v[0:3], v[170:173], v[202:205], v[0:3]
	v_mfma_f32_16x16x32_bf16 v[28:31], v[166:169], v[182:185], v[28:31]
	v_mfma_f32_16x16x32_bf16 v[24:27], v[174:177], v[182:185], v[24:27]
	v_mfma_f32_16x16x32_bf16 v[20:23], v[166:169], v[190:193], v[20:23]
	v_mfma_f32_16x16x32_bf16 v[16:19], v[174:177], v[190:193], v[16:19]
	v_mfma_f32_16x16x32_bf16 v[12:15], v[166:169], v[198:201], v[12:15]
	v_mfma_f32_16x16x32_bf16 v[8:11], v[174:177], v[198:201], v[8:11]
	v_mfma_f32_16x16x32_bf16 v[4:7], v[166:169], v[206:209], v[4:7]
	v_mfma_f32_16x16x32_bf16 v[0:3], v[174:177], v[206:209], v[0:3]
	s_setprio 0
	s_barrier
	ds_read_b128 v[146:149], v139
	ds_read_b128 v[150:153], v139 offset:1024
	ds_read_b128 v[154:157], v139 offset:2048
	ds_read_b128 v[158:161], v139 offset:3072
	ds_read_b128 v[162:165], v138
	ds_read_b128 v[166:169], v138 offset:1024
	ds_read_b128 v[170:173], v138 offset:2048
	ds_read_b128 v[174:177], v138 offset:3072
	s_mov_b32 m0, s34
	v_lshl_add_u64 v[218:219], v[214:215], 0, s[26:27]
	ds_read_b128 v[178:181], v137 offset:32768
	ds_read_b128 v[182:185], v137 offset:33792
	ds_read_b128 v[186:189], v137 offset:34816
	ds_read_b128 v[190:193], v137 offset:35840
	ds_read_b128 v[194:197], v137 offset:36864
	ds_read_b128 v[198:201], v137 offset:37888
	ds_read_b128 v[202:205], v137 offset:38912
	ds_read_b128 v[206:209], v137 offset:39936
	global_load_lds_dwordx4 v[218:219], off
	v_lshl_add_u64 v[218:219], v[216:217], 0, s[26:27]
	s_mov_b32 m0, s35
	s_nop 0
	global_load_lds_dwordx4 v[218:219], off
	s_waitcnt vmcnt(8)
	s_waitcnt lgkmcnt(0)
	s_barrier
	s_setprio 1
	v_mfma_f32_16x16x32_bf16 v[124:127], v[146:149], v[178:181], v[124:127]
	v_mfma_f32_16x16x32_bf16 v[120:123], v[154:157], v[178:181], v[120:123]
	v_mfma_f32_16x16x32_bf16 v[116:119], v[146:149], v[186:189], v[116:119]
	v_mfma_f32_16x16x32_bf16 v[112:115], v[154:157], v[186:189], v[112:115]
	v_mfma_f32_16x16x32_bf16 v[108:111], v[146:149], v[194:197], v[108:111]
	v_mfma_f32_16x16x32_bf16 v[104:107], v[154:157], v[194:197], v[104:107]
	v_mfma_f32_16x16x32_bf16 v[100:103], v[146:149], v[202:205], v[100:103]
	v_mfma_f32_16x16x32_bf16 v[96:99], v[154:157], v[202:205], v[96:99]
	v_mfma_f32_16x16x32_bf16 v[124:127], v[150:153], v[182:185], v[124:127]
	v_mfma_f32_16x16x32_bf16 v[120:123], v[158:161], v[182:185], v[120:123]
	v_mfma_f32_16x16x32_bf16 v[116:119], v[150:153], v[190:193], v[116:119]
	v_mfma_f32_16x16x32_bf16 v[112:115], v[158:161], v[190:193], v[112:115]
	v_mfma_f32_16x16x32_bf16 v[108:111], v[150:153], v[198:201], v[108:111]
	v_mfma_f32_16x16x32_bf16 v[104:107], v[158:161], v[198:201], v[104:107]
	v_mfma_f32_16x16x32_bf16 v[100:103], v[150:153], v[206:209], v[100:103]
	v_mfma_f32_16x16x32_bf16 v[96:99], v[158:161], v[206:209], v[96:99]
	v_mfma_f32_16x16x32_bf16 v[92:95], v[162:165], v[178:181], v[92:95]
	v_mfma_f32_16x16x32_bf16 v[88:91], v[170:173], v[178:181], v[88:91]
	v_mfma_f32_16x16x32_bf16 v[84:87], v[162:165], v[186:189], v[84:87]
	v_mfma_f32_16x16x32_bf16 v[80:83], v[170:173], v[186:189], v[80:83]
	v_mfma_f32_16x16x32_bf16 v[76:79], v[162:165], v[194:197], v[76:79]
	v_mfma_f32_16x16x32_bf16 v[72:75], v[170:173], v[194:197], v[72:75]
	v_mfma_f32_16x16x32_bf16 v[68:71], v[162:165], v[202:205], v[68:71]
	v_mfma_f32_16x16x32_bf16 v[64:67], v[170:173], v[202:205], v[64:67]
	v_mfma_f32_16x16x32_bf16 v[92:95], v[166:169], v[182:185], v[92:95]
	v_mfma_f32_16x16x32_bf16 v[88:91], v[174:177], v[182:185], v[88:91]
	v_mfma_f32_16x16x32_bf16 v[84:87], v[166:169], v[190:193], v[84:87]
	v_mfma_f32_16x16x32_bf16 v[80:83], v[174:177], v[190:193], v[80:83]
	v_mfma_f32_16x16x32_bf16 v[76:79], v[166:169], v[198:201], v[76:79]
	v_mfma_f32_16x16x32_bf16 v[72:75], v[174:177], v[198:201], v[72:75]
	v_mfma_f32_16x16x32_bf16 v[68:71], v[166:169], v[206:209], v[68:71]
	v_mfma_f32_16x16x32_bf16 v[64:67], v[174:177], v[206:209], v[64:67]
	s_setprio 0
	s_barrier
; template <int ROT, class Epi0, class Epi1, class Late, class Post0>
; __device__ __forceinline__ void gemm_phase_pair(PG8_LAS unsigned char* lds, const Gemm g0, const Gemm g1, const Unit u, const Epi0& E0, const Epi1& E1, int wid_in, const Late& late, const Post0& post0) {
;     ...
;     for (int t = t_late; t < nt0 - 2; t += 2) {
;         if constexpr (Epi0::HAS_MID) { if (t == nt0 / 2) E0.mid(acc, u, wr, wc, fr, fq); }
;         const char* a1 = cA + PG8_KT(t + 1); const char* a2 = cA + PG8_KT(t + 2); const char* b2 = cB + PG8_KT(t + 2); const char* a3 = cA + PG8_KT(t + 3); const char* b3 = cB + PG8_KT(t + 3);
;         PG8_PAIR_ITER(a1 + hs0, vA0, a2, b2, a3, b3, vA0, vB0, hs0);
;     }
	s_mov_b32 m0, s44
	v_lshl_add_u64 v[218:219], v[210:211], 0, s[28:29]
	ds_read_b128 v[178:181], v137 offset:49152
	ds_read_b128 v[182:185], v137 offset:50176
	ds_read_b128 v[186:189], v137 offset:51200
	ds_read_b128 v[190:193], v137 offset:52224
	ds_read_b128 v[194:197], v137 offset:53248
	ds_read_b128 v[198:201], v137 offset:54272
	ds_read_b128 v[202:205], v137 offset:55296
	ds_read_b128 v[206:209], v137 offset:56320
	global_load_lds_dwordx4 v[218:219], off
	v_lshl_add_u64 v[218:219], v[212:213], 0, s[28:29]
	s_mov_b32 m0, s42
	v_lshl_add_u64 v[210:211], v[210:211], 0, s[30:31]
	global_load_lds_dwordx4 v[218:219], off
	s_mov_b32 m0, s43
	s_nop 0
	global_load_lds_dwordx4 v[210:211], off
	v_lshl_add_u64 v[210:211], v[212:213], 0, s[30:31]
	s_mov_b32 m0, s41
	s_nop 0
	global_load_lds_dwordx4 v[210:211], off
	v_lshl_add_u64 v[210:211], v[214:215], 0, s[36:37]
	s_mov_b32 m0, s13
	s_nop 0
	global_load_lds_dwordx4 v[210:211], off
	v_lshl_add_u64 v[210:211], v[216:217], 0, s[36:37]
	s_mov_b32 m0, s33
	s_nop 0
	global_load_lds_dwordx4 v[210:211], off
	s_waitcnt vmcnt(8)
	s_waitcnt lgkmcnt(0)
	s_barrier
	s_setprio 1
	v_mfma_f32_16x16x32_bf16 v[60:63], v[146:149], v[178:181], v[60:63]
	v_mfma_f32_16x16x32_bf16 v[56:59], v[154:157], v[178:181], v[56:59]
	v_mfma_f32_16x16x32_bf16 v[52:55], v[146:149], v[186:189], v[52:55]
	v_mfma_f32_16x16x32_bf16 v[48:51], v[154:157], v[186:189], v[48:51]
	v_mfma_f32_16x16x32_bf16 v[44:47], v[146:149], v[194:197], v[44:47]
	v_mfma_f32_16x16x32_bf16 v[40:43], v[154:157], v[194:197], v[40:43]
	v_mfma_f32_16x16x32_bf16 v[36:39], v[146:149], v[202:205], v[36:39]
	v_mfma_f32_16x16x32_bf16 v[32:35], v[154:157], v[202:205], v[32:35]
	v_mfma_f32_16x16x32_bf16 v[60:63], v[150:153], v[182:185], v[60:63]
	v_mfma_f32_16x16x32_bf16 v[56:59], v[158:161], v[182:185], v[56:59]
	v_mfma_f32_16x16x32_bf16 v[52:55], v[150:153], v[190:193], v[52:55]
	v_mfma_f32_16x16x32_bf16 v[48:51], v[158:161], v[190:193], v[48:51]
	v_mfma_f32_16x16x32_bf16 v[44:47], v[150:153], v[198:201], v[44:47]
	v_mfma_f32_16x16x32_bf16 v[40:43], v[158:161], v[198:201], v[40:43]
	v_mfma_f32_16x16x32_bf16 v[36:39], v[150:153], v[206:209], v[36:39]
	v_mfma_f32_16x16x32_bf16 v[32:35], v[158:161], v[206:209], v[32:35]
	v_mfma_f32_16x16x32_bf16 v[28:31], v[162:165], v[178:181], v[28:31]
	v_mfma_f32_16x16x32_bf16 v[24:27], v[170:173], v[178:181], v[24:27]
	v_mfma_f32_16x16x32_bf16 v[20:23], v[162:165], v[186:189], v[20:23]
	v_mfma_f32_16x16x32_bf16 v[16:19], v[170:173], v[186:189], v[16:19]
	v_mfma_f32_16x16x32_bf16 v[12:15], v[162:165], v[194:197], v[12:15]
	v_mfma_f32_16x16x32_bf16 v[8:11], v[170:173], v[194:197], v[8:11]
	v_mfma_f32_16x16x32_bf16 v[4:7], v[162:165], v[202:205], v[4:7]
	v_mfma_f32_16x16x32_bf16 v[0:3], v[170:173], v[202:205], v[0:3]
	v_mfma_f32_16x16x32_bf16 v[28:31], v[166:169], v[182:185], v[28:31]
	v_mfma_f32_16x16x32_bf16 v[24:27], v[174:177], v[182:185], v[24:27]
	v_mfma_f32_16x16x32_bf16 v[20:23], v[166:169], v[190:193], v[20:23]
	v_mfma_f32_16x16x32_bf16 v[16:19], v[174:177], v[190:193], v[16:19]
	v_mfma_f32_16x16x32_bf16 v[12:15], v[166:169], v[198:201], v[12:15]
	v_mfma_f32_16x16x32_bf16 v[8:11], v[174:177], v[198:201], v[8:11]
	v_mfma_f32_16x16x32_bf16 v[4:7], v[166:169], v[206:209], v[4:7]
	v_mfma_f32_16x16x32_bf16 v[0:3], v[174:177], v[206:209], v[0:3]
	s_setprio 0
	s_barrier
	s_add_i32 s62, s62, 2
	s_add_u32 s18, s18, 0x100
	s_addc_u32 s19, s19, 0
	s_cmp_gt_u32 s62, 27
	s_cbranch_scc1 .LBB0_877

.LBB0_877:
	v_mbcnt_lo_u32_b32 v129, -1, 0
	v_mbcnt_hi_u32_b32 v129, -1, v129
	s_mov_b32 s20, 0x7fffe0
	v_add_u32_e32 v129, s60, v129
	v_ashrrev_i32_e32 v132, 31, v129
	v_lshrrev_b32_e32 v132, 26, v132
	v_lshlrev_b32_e32 v131, 4, v129
	v_add_u32_e32 v132, v129, v132
	v_bfe_i32 v129, v129, 27, 1
	v_lshrrev_b32_e32 v129, 22, v129
	v_add_u32_e32 v129, v131, v129
	v_and_b32_e32 v129, 0xfffffc00, v129
	v_sub_u32_e32 v129, v131, v129
	v_lshrrev_b32_e32 v133, 4, v129
	v_bitop3_b32 v129, v133, v129, 32 bitop3:0x6c
	v_ashrrev_i32_e32 v134, 31, v129
	v_ashrrev_i32_e32 v132, 6, v132
	v_lshrrev_b32_e32 v134, 26, v134
	v_lshlrev_b32_e32 v133, 3, v132
	v_add_u32_e32 v134, v129, v134
	v_and_b32_e32 v133, -16, v133
	v_ashrrev_i32_e32 v135, 6, v134
	v_and_b32_e32 v134, 0xc0, v134
	v_add_u32_e32 v133, v135, v133
	v_sub_u32_e32 v129, v129, v134
	v_mov_b32_e32 v134, 1
	v_lshlrev_b32_e32 v132, 5, v132
	v_ashrrev_i16_sdwa v129, v134, sext(v129) dst_sel:DWORD dst_unused:UNUSED_PAD src0_sel:DWORD src1_sel:BYTE_0
	v_lshlrev_b32_e32 v144, 1, v133
	v_lshrrev_b32_e32 v145, 2, v133
	v_and_b32_e32 v135, 3, v135
	v_and_b32_e32 v132, 32, v132
	v_bfe_i32 v129, v129, 0, 16
	v_and_b32_e32 v144, 24, v144
	v_and_b32_e32 v145, 4, v145
	v_and_or_b32 v135, v133, s20, v135
	v_or3_b32 v135, v135, v145, v144
	v_add_lshl_u32 v129, v132, v129, 1
	v_lshl_add_u32 v228, v133, 9, v129
	v_lshl_add_u32 v132, v135, 9, v129
	v_add_u32_e32 v129, 0x2000, v131
	v_ashrrev_i32_e32 v131, 31, v129
	v_lshrrev_b32_e32 v131, 22, v131
	v_add_u32_e32 v131, v129, v131
	v_ashrrev_i32_e32 v131, 10, v131
	v_mul_i32_i24_e32 v133, 0x400, v131
	v_sub_u32_e32 v129, v129, v133
	v_lshrrev_b32_e32 v133, 4, v129
	v_bitop3_b32 v129, v133, v129, 32 bitop3:0x6c
	v_ashrrev_i32_e32 v135, 31, v129
	v_lshrrev_b32_e32 v135, 26, v135
	v_lshlrev_b32_e32 v133, 3, v131
	v_add_u32_e32 v135, v129, v135
	v_and_b32_e32 v133, -16, v133
	v_ashrrev_i32_e32 v144, 6, v135
	v_and_b32_e32 v135, 0xc0, v135
	v_add_u32_e32 v133, v144, v133
	v_sub_u32_e32 v129, v129, v135
	v_lshlrev_b32_e32 v131, 5, v131
	v_ashrrev_i16_sdwa v129, v134, sext(v129) dst_sel:DWORD dst_unused:UNUSED_PAD src0_sel:DWORD src1_sel:BYTE_0
	v_lshlrev_b32_e32 v134, 1, v133
	v_lshrrev_b32_e32 v135, 2, v133
	v_and_b32_e32 v144, 3, v144
	v_and_b32_e32 v131, 32, v131
	v_bfe_i32 v129, v129, 0, 16
	v_and_b32_e32 v134, 24, v134
	v_and_b32_e32 v135, 4, v135
	v_and_or_b32 v144, v133, s20, v144
	v_or3_b32 v134, v144, v135, v134
	v_add_lshl_u32 v129, v131, v129, 1
	v_lshl_add_u32 v230, v133, 9, v129
	v_lshl_add_u32 v134, v134, 9, v129
	ds_read_b128 v[144:147], v141
	ds_read_b128 v[148:151], v141 offset:1024
	ds_read_b128 v[152:155], v141 offset:2048
	ds_read_b128 v[156:159], v141 offset:3072
	ds_read_b128 v[160:163], v140
	ds_read_b128 v[164:167], v140 offset:1024
	ds_read_b128 v[168:171], v140 offset:2048
	ds_read_b128 v[172:175], v140 offset:3072
	s_lshl_b64 s[14:15], s[14:15], 17
	s_lshl_b64 s[18:19], s[8:9], 17
	s_add_u32 s9, s96, s14
	s_addc_u32 s21, s97, s15
	s_add_u32 s14, s9, 0x3400000
	s_addc_u32 s15, s21, 0
	s_add_u32 s22, s96, s18
	s_addc_u32 s23, s97, s19
	s_add_u32 s18, s22, 0x1300000
	s_addc_u32 s19, s23, 0
	s_add_u32 s16, s16, 0x80780
	s_addc_u32 s17, s17, 0
	s_mov_b32 m0, s51
	ds_read_b128 v[176:179], v137
	ds_read_b128 v[180:183], v137 offset:1024
	ds_read_b128 v[184:187], v137 offset:2048
	ds_read_b128 v[188:191], v137 offset:3072
	ds_read_b128 v[192:195], v137 offset:4096
	ds_read_b128 v[196:199], v137 offset:5120
	ds_read_b128 v[200:203], v137 offset:6144
	ds_read_b128 v[204:207], v137 offset:7168
	global_load_lds_dwordx4 v130, s[16:17]
	s_mov_b32 m0, s50
	s_nop 0
	global_load_lds_dwordx4 v128, s[16:17]
	s_waitcnt vmcnt(8)
	s_waitcnt lgkmcnt(0)
	s_barrier
	s_setprio 1
	v_mfma_f32_16x16x32_bf16 v[124:127], v[144:147], v[176:179], v[124:127]
	v_mfma_f32_16x16x32_bf16 v[120:123], v[152:155], v[176:179], v[120:123]
	v_mfma_f32_16x16x32_bf16 v[116:119], v[144:147], v[184:187], v[116:119]
	v_mfma_f32_16x16x32_bf16 v[112:115], v[152:155], v[184:187], v[112:115]
	v_mfma_f32_16x16x32_bf16 v[100:103], v[144:147], v[200:203], v[100:103]
	v_mfma_f32_16x16x32_bf16 v[96:99], v[152:155], v[200:203], v[96:99]
	v_mfma_f32_16x16x32_bf16 v[124:127], v[148:151], v[180:183], v[124:127]
	v_mfma_f32_16x16x32_bf16 v[120:123], v[156:159], v[180:183], v[120:123]
	v_mfma_f32_16x16x32_bf16 v[116:119], v[148:151], v[188:191], v[116:119]
	v_mfma_f32_16x16x32_bf16 v[112:115], v[156:159], v[188:191], v[112:115]
	v_mfma_f32_16x16x32_bf16 v[108:111], v[144:147], v[192:195], v[108:111]
	v_mfma_f32_16x16x32_bf16 v[104:107], v[152:155], v[192:195], v[104:107]
	v_mfma_f32_16x16x32_bf16 v[100:103], v[148:151], v[204:207], v[100:103]
	v_mfma_f32_16x16x32_bf16 v[96:99], v[156:159], v[204:207], v[96:99]
	v_mfma_f32_16x16x32_bf16 v[128:131], v[148:151], v[196:199], v[108:111]
	v_mfma_f32_16x16x32_bf16 v[208:211], v[156:159], v[196:199], v[104:107]
	v_mfma_f32_16x16x32_bf16 v[84:87], v[160:163], v[184:187], v[84:87]
	v_mfma_f32_16x16x32_bf16 v[80:83], v[168:171], v[184:187], v[80:83]
	v_mfma_f32_16x16x32_bf16 v[68:71], v[160:163], v[200:203], v[68:71]
	v_mfma_f32_16x16x32_bf16 v[64:67], v[168:171], v[200:203], v[64:67]
	v_mfma_f32_16x16x32_bf16 v[92:95], v[160:163], v[176:179], v[92:95]
	v_mfma_f32_16x16x32_bf16 v[88:91], v[168:171], v[176:179], v[88:91]
	v_mfma_f32_16x16x32_bf16 v[84:87], v[164:167], v[188:191], v[84:87]
	v_mfma_f32_16x16x32_bf16 v[80:83], v[172:175], v[188:191], v[80:83]
	v_mfma_f32_16x16x32_bf16 v[76:79], v[160:163], v[192:195], v[76:79]
	v_mfma_f32_16x16x32_bf16 v[72:75], v[168:171], v[192:195], v[72:75]
	v_mfma_f32_16x16x32_bf16 v[68:71], v[164:167], v[204:207], v[68:71]
	v_mfma_f32_16x16x32_bf16 v[64:67], v[172:175], v[204:207], v[64:67]
	v_mfma_f32_16x16x32_bf16 v[212:215], v[164:167], v[180:183], v[92:95]
	v_mfma_f32_16x16x32_bf16 v[176:179], v[172:175], v[180:183], v[88:91]
	v_mfma_f32_16x16x32_bf16 v[180:183], v[164:167], v[196:199], v[76:79]
	v_mfma_f32_16x16x32_bf16 v[184:187], v[172:175], v[196:199], v[72:75]
	s_setprio 0
	s_barrier
	s_mov_b32 m0, s49
	ds_read_b128 v[72:75], v137 offset:16384
	ds_read_b128 v[76:79], v137 offset:17408
	ds_read_b128 v[88:91], v137 offset:18432
	ds_read_b128 v[92:95], v137 offset:19456
	ds_read_b128 v[104:107], v137 offset:20480
	ds_read_b128 v[108:111], v137 offset:21504
	ds_read_b128 v[188:191], v137 offset:22528
	ds_read_b128 v[192:195], v137 offset:23552
	global_load_lds_dwordx4 v132, s[18:19]
	s_mov_b32 m0, s47
	s_add_u32 s16, s22, 0x1310000
	global_load_lds_dwordx4 v134, s[18:19]
	s_addc_u32 s17, s23, 0
	s_mov_b32 m0, s48
	v_mov_b32_e32 v133, 0
	global_load_lds_dwordx4 v132, s[16:17]
	s_mov_b32 m0, s46
	v_mov_b32_e32 v135, v133
	global_load_lds_dwordx4 v134, s[16:17]
	s_mov_b32 m0, s40
	v_mov_b32_e32 v229, v133
	global_load_lds_dwordx4 v228, s[14:15]
	s_mov_b32 m0, s45
	v_mov_b32_e32 v231, v133
	global_load_lds_dwordx4 v230, s[14:15]
	s_waitcnt vmcnt(8)
	s_waitcnt lgkmcnt(0)
	v_lshl_add_u64 v[232:233], s[18:19], 0, v[132:133]
	v_lshl_add_u64 v[234:235], s[18:19], 0, v[134:135]
	v_lshl_add_u64 v[236:237], s[14:15], 0, v[228:229]
	v_lshl_add_u64 v[238:239], s[14:15], 0, v[230:231]
	s_barrier
	s_setprio 1
	v_mfma_f32_16x16x32_bf16 v[52:55], v[144:147], v[88:91], v[52:55]
	v_mfma_f32_16x16x32_bf16 v[48:51], v[152:155], v[88:91], v[48:51]
	v_mfma_f32_16x16x32_bf16 v[36:39], v[144:147], v[188:191], v[36:39]
	v_mfma_f32_16x16x32_bf16 v[32:35], v[152:155], v[188:191], v[32:35]
	v_mfma_f32_16x16x32_bf16 v[60:63], v[144:147], v[72:75], v[60:63]
	v_mfma_f32_16x16x32_bf16 v[56:59], v[152:155], v[72:75], v[56:59]
	v_mfma_f32_16x16x32_bf16 v[52:55], v[148:151], v[92:95], v[52:55]
	v_mfma_f32_16x16x32_bf16 v[48:51], v[156:159], v[92:95], v[48:51]
	v_mfma_f32_16x16x32_bf16 v[44:47], v[144:147], v[104:107], v[44:47]
	v_mfma_f32_16x16x32_bf16 v[40:43], v[152:155], v[104:107], v[40:43]
	v_mfma_f32_16x16x32_bf16 v[36:39], v[148:151], v[192:195], v[36:39]
	v_mfma_f32_16x16x32_bf16 v[32:35], v[156:159], v[192:195], v[32:35]
	v_mfma_f32_16x16x32_bf16 v[196:199], v[148:151], v[76:79], v[60:63]
	v_mfma_f32_16x16x32_bf16 v[200:203], v[156:159], v[76:79], v[56:59]
	v_mfma_f32_16x16x32_bf16 v[204:207], v[148:151], v[108:111], v[44:47]
	v_mfma_f32_16x16x32_bf16 v[216:219], v[156:159], v[108:111], v[40:43]
	v_mfma_f32_16x16x32_bf16 v[20:23], v[160:163], v[88:91], v[20:23]
	v_mfma_f32_16x16x32_bf16 v[16:19], v[168:171], v[88:91], v[16:19]
	v_mfma_f32_16x16x32_bf16 v[4:7], v[160:163], v[188:191], v[4:7]
	v_mfma_f32_16x16x32_bf16 v[0:3], v[168:171], v[188:191], v[0:3]
	v_mfma_f32_16x16x32_bf16 v[28:31], v[160:163], v[72:75], v[28:31]
	v_mfma_f32_16x16x32_bf16 v[24:27], v[168:171], v[72:75], v[24:27]
	v_mfma_f32_16x16x32_bf16 v[20:23], v[164:167], v[92:95], v[20:23]
	v_mfma_f32_16x16x32_bf16 v[16:19], v[172:175], v[92:95], v[16:19]
	v_mfma_f32_16x16x32_bf16 v[12:15], v[160:163], v[104:107], v[12:15]
	v_mfma_f32_16x16x32_bf16 v[8:11], v[168:171], v[104:107], v[8:11]
	v_mfma_f32_16x16x32_bf16 v[4:7], v[164:167], v[192:195], v[4:7]
	v_mfma_f32_16x16x32_bf16 v[0:3], v[172:175], v[192:195], v[0:3]
	v_mfma_f32_16x16x32_bf16 v[144:147], v[164:167], v[76:79], v[28:31]
	v_mfma_f32_16x16x32_bf16 v[148:151], v[172:175], v[76:79], v[24:27]
	v_mfma_f32_16x16x32_bf16 v[152:155], v[164:167], v[108:111], v[12:15]
	v_mfma_f32_16x16x32_bf16 v[156:159], v[172:175], v[108:111], v[8:11]
	s_setprio 0
	s_barrier
	s_nop 0
	ds_read_b128 v[8:11], v139
	ds_read_b128 v[12:15], v139 offset:1024
	ds_read_b128 v[160:163], v139 offset:2048
	ds_read_b128 v[164:167], v139 offset:3072
	ds_read_b128 v[168:171], v138
	ds_read_b128 v[172:175], v138 offset:1024
	ds_read_b128 v[188:191], v138 offset:2048
	ds_read_b128 v[192:195], v138 offset:3072
	s_add_u32 s20, s9, 0x3410000
	s_addc_u32 s21, s21, 0
	s_mov_b32 m0, s34
	ds_read_b128 v[24:27], v137 offset:32768
	ds_read_b128 v[28:31], v137 offset:33792
	ds_read_b128 v[40:43], v137 offset:34816
	ds_read_b128 v[44:47], v137 offset:35840
	ds_read_b128 v[56:59], v137 offset:36864
	ds_read_b128 v[60:63], v137 offset:37888
	ds_read_b128 v[220:223], v137 offset:38912
	ds_read_b128 v[224:227], v137 offset:39936
	global_load_lds_dwordx4 v228, s[20:21]
	s_mov_b32 m0, s35
	s_nop 0
	global_load_lds_dwordx4 v230, s[20:21]
	s_waitcnt vmcnt(8)
	s_waitcnt lgkmcnt(0)
	s_barrier
; #define PG8_BAR __builtin_amdgcn_s_barrier()
; template <int ROT, class Epi0, class Epi1, class Late, class Post0>
; __device__ __forceinline__ void gemm_phase_pair(PG8_LAS unsigned char* lds, const Gemm g0, const Gemm g1, const Unit u, const Epi0& E0, const Epi1& E1, int wid_in, const Late& late, const Post0& post0) {
;     ...
;     if (wr == 0) PG8_BAR;
	s_setprio 1
	v_mfma_f32_16x16x32_bf16 v[72:75], v[8:11], v[24:27], v[124:127]
	v_mfma_f32_16x16x32_bf16 v[124:127], v[12:15], v[28:31], v[72:75]
	v_mfma_f32_16x16x32_bf16 v[72:75], v[160:163], v[24:27], v[120:123]
	v_mfma_f32_16x16x32_bf16 v[120:123], v[164:167], v[28:31], v[72:75]
	v_mfma_f32_16x16x32_bf16 v[72:75], v[8:11], v[40:43], v[116:119]
	v_mfma_f32_16x16x32_bf16 v[108:111], v[12:15], v[44:47], v[72:75]
	v_mfma_f32_16x16x32_bf16 v[72:75], v[160:163], v[40:43], v[112:115]
	v_mfma_f32_16x16x32_bf16 v[104:107], v[164:167], v[44:47], v[72:75]
	v_mfma_f32_16x16x32_bf16 v[72:75], v[8:11], v[56:59], v[128:131]
	v_mfma_f32_16x16x32_bf16 v[92:95], v[12:15], v[60:63], v[72:75]
	v_mfma_f32_16x16x32_bf16 v[72:75], v[160:163], v[56:59], v[208:211]
	v_mfma_f32_16x16x32_bf16 v[88:91], v[164:167], v[60:63], v[72:75]
	v_mfma_f32_16x16x32_bf16 v[72:75], v[8:11], v[220:223], v[100:103]
	v_mfma_f32_16x16x32_bf16 v[76:79], v[12:15], v[224:227], v[72:75]
	v_mfma_f32_16x16x32_bf16 v[72:75], v[160:163], v[220:223], v[96:99]
	v_mfma_f32_16x16x32_bf16 v[72:75], v[164:167], v[224:227], v[72:75]
	v_mfma_f32_16x16x32_bf16 v[96:99], v[168:171], v[24:27], v[212:215]
	v_mfma_f32_16x16x32_bf16 v[24:27], v[188:191], v[24:27], v[176:179]
	v_mfma_f32_16x16x32_bf16 v[116:119], v[192:195], v[28:31], v[24:27]
	v_mfma_f32_16x16x32_bf16 v[24:27], v[168:171], v[40:43], v[84:87]
	v_mfma_f32_16x16x32_bf16 v[112:115], v[172:175], v[28:31], v[96:99]
	v_mfma_f32_16x16x32_bf16 v[96:99], v[172:175], v[44:47], v[24:27]
	v_mfma_f32_16x16x32_bf16 v[24:27], v[188:191], v[40:43], v[80:83]
	v_mfma_f32_16x16x32_bf16 v[100:103], v[192:195], v[44:47], v[24:27]
	v_mfma_f32_16x16x32_bf16 v[24:27], v[168:171], v[56:59], v[180:183]
	v_mfma_f32_16x16x32_bf16 v[80:83], v[172:175], v[60:63], v[24:27]
	v_mfma_f32_16x16x32_bf16 v[24:27], v[188:191], v[56:59], v[184:187]
	v_mfma_f32_16x16x32_bf16 v[84:87], v[192:195], v[60:63], v[24:27]
	v_mfma_f32_16x16x32_bf16 v[24:27], v[168:171], v[220:223], v[68:71]
	v_mfma_f32_16x16x32_bf16 v[56:59], v[172:175], v[224:227], v[24:27]
	v_mfma_f32_16x16x32_bf16 v[24:27], v[188:191], v[220:223], v[64:67]
	v_mfma_f32_16x16x32_bf16 v[60:63], v[192:195], v[224:227], v[24:27]
	s_setprio 0
	s_barrier
	s_mov_b64 s[24:25], 0x80
	s_mov_b32 m0, s44
	s_nop 2
	v_lshl_add_u64 v[24:25], v[232:233], 0, s[24:25]
	ds_read_b128 v[128:131], v137 offset:49152
	ds_read_b128 v[176:179], v137 offset:50176
	ds_read_b128 v[180:183], v137 offset:51200
	ds_read_b128 v[184:187], v137 offset:52224
	ds_read_b128 v[208:211], v137 offset:53248
	ds_read_b128 v[212:215], v137 offset:54272
	ds_read_b128 v[220:223], v137 offset:55296
	ds_read_b128 v[224:227], v137 offset:56320
	global_load_lds_dwordx4 v[24:25], off
	v_lshl_add_u64 v[24:25], v[234:235], 0, s[24:25]
	s_mov_b32 m0, s42
	s_add_u32 s22, s22, 0x1310080
	global_load_lds_dwordx4 v[24:25], off
	s_addc_u32 s23, s23, 0
	s_mov_b32 m0, s43
	v_lshl_add_u64 v[24:25], v[236:237], 0, s[24:25]
	global_load_lds_dwordx4 v132, s[22:23]
	s_mov_b32 m0, s41
	s_nop 0
	global_load_lds_dwordx4 v134, s[22:23]
	s_mov_b32 m0, s13
	s_nop 0
	global_load_lds_dwordx4 v[24:25], off
	v_lshl_add_u64 v[24:25], v[238:239], 0, s[24:25]
	s_mov_b32 m0, s33
	s_nop 0
	global_load_lds_dwordx4 v[24:25], off
	s_waitcnt vmcnt(8)
	s_waitcnt lgkmcnt(0)
	s_barrier
	s_setprio 1
	v_mfma_f32_16x16x32_bf16 v[24:27], v[8:11], v[128:131], v[196:199]
	v_mfma_f32_16x16x32_bf16 v[68:71], v[12:15], v[176:179], v[24:27]
	v_mfma_f32_16x16x32_bf16 v[24:27], v[160:163], v[128:131], v[200:203]
	v_mfma_f32_16x16x32_bf16 v[64:67], v[164:167], v[176:179], v[24:27]
	v_mfma_f32_16x16x32_bf16 v[24:27], v[8:11], v[180:183], v[52:55]
	v_mfma_f32_16x16x32_bf16 v[44:47], v[12:15], v[184:187], v[24:27]
	v_mfma_f32_16x16x32_bf16 v[24:27], v[160:163], v[180:183], v[48:51]
	v_mfma_f32_16x16x32_bf16 v[40:43], v[164:167], v[184:187], v[24:27]
	v_mfma_f32_16x16x32_bf16 v[24:27], v[8:11], v[208:211], v[204:207]
	v_mfma_f32_16x16x32_bf16 v[8:11], v[8:11], v[220:223], v[36:39]
	v_mfma_f32_16x16x32_bf16 v[28:31], v[12:15], v[212:215], v[24:27]
	v_mfma_f32_16x16x32_bf16 v[24:27], v[160:163], v[208:211], v[216:219]
	v_mfma_f32_16x16x32_bf16 v[12:15], v[12:15], v[224:227], v[8:11]
	v_mfma_f32_16x16x32_bf16 v[8:11], v[160:163], v[220:223], v[32:35]
	v_mfma_f32_16x16x32_bf16 v[24:27], v[164:167], v[212:215], v[24:27]
	v_mfma_f32_16x16x32_bf16 v[8:11], v[164:167], v[224:227], v[8:11]
	v_mfma_f32_16x16x32_bf16 v[32:35], v[168:171], v[128:131], v[144:147]
	v_mfma_f32_16x16x32_bf16 v[48:51], v[172:175], v[176:179], v[32:35]
	v_mfma_f32_16x16x32_bf16 v[32:35], v[188:191], v[128:131], v[148:151]
	v_mfma_f32_16x16x32_bf16 v[20:23], v[168:171], v[180:183], v[20:23]
	v_mfma_f32_16x16x32_bf16 v[16:19], v[188:191], v[180:183], v[16:19]
	v_mfma_f32_16x16x32_bf16 v[52:55], v[192:195], v[176:179], v[32:35]
	v_mfma_f32_16x16x32_bf16 v[32:35], v[172:175], v[184:187], v[20:23]
	v_mfma_f32_16x16x32_bf16 v[36:39], v[192:195], v[184:187], v[16:19]
	v_mfma_f32_16x16x32_bf16 v[16:19], v[168:171], v[208:211], v[152:155]
	v_mfma_f32_16x16x32_bf16 v[20:23], v[188:191], v[208:211], v[156:159]
	v_mfma_f32_16x16x32_bf16 v[4:7], v[168:171], v[220:223], v[4:7]
	v_mfma_f32_16x16x32_bf16 v[0:3], v[188:191], v[220:223], v[0:3]
	v_mfma_f32_16x16x32_bf16 v[16:19], v[172:175], v[212:215], v[16:19]
	v_mfma_f32_16x16x32_bf16 v[20:23], v[192:195], v[212:215], v[20:23]
	v_mfma_f32_16x16x32_bf16 v[4:7], v[172:175], v[224:227], v[4:7]
	v_mfma_f32_16x16x32_bf16 v[0:3], v[192:195], v[224:227], v[0:3]
	s_setprio 0
	s_barrier
	s_and_b64 vcc, exec, s[4:5]
	s_cbranch_vccz .LBB0_879
	s_barrier

.LBB0_886:
	v_mbcnt_lo_u32_b32 v0, -1, 0
	v_mbcnt_hi_u32_b32 v0, -1, v0
	v_mov_b32_e32 v6, 1
	v_add_u32_e32 v0, s60, v0
	v_ashrrev_i32_e32 v2, 31, v0
	v_lshrrev_b32_e32 v2, 26, v2
	v_lshlrev_b32_e32 v1, 4, v0
	v_add_u32_e32 v2, v0, v2
	v_bfe_i32 v0, v0, 27, 1
	v_lshrrev_b32_e32 v0, 22, v0
	v_add_u32_e32 v0, v1, v0
	v_and_b32_e32 v0, 0xfffffc00, v0
	v_sub_u32_e32 v0, v1, v0
	v_lshrrev_b32_e32 v3, 4, v0
	v_bitop3_b32 v0, v3, v0, 32 bitop3:0x6c
	v_ashrrev_i32_e32 v4, 31, v0
	v_lshrrev_b32_e32 v4, 26, v4
	v_add_u32_e32 v4, v0, v4
	v_ashrrev_i32_e32 v5, 6, v4
	v_and_b32_e32 v4, 0xc0, v4
	v_ashrrev_i32_e32 v2, 6, v2
	v_sub_u32_e32 v0, v0, v4
	v_lshlrev_b32_e32 v3, 3, v2
	v_lshlrev_b32_e32 v2, 5, v2
	v_ashrrev_i16_sdwa v0, v6, sext(v0) dst_sel:DWORD dst_unused:UNUSED_PAD src0_sel:DWORD src1_sel:BYTE_0
	v_and_b32_e32 v2, 32, v2
	v_bfe_i32 v0, v0, 0, 16
	v_add_u32_e32 v1, 0x2000, v1
	v_and_b32_e32 v3, -16, v3
	v_add_lshl_u32 v0, v2, v0, 1
	v_ashrrev_i32_e32 v2, 31, v1
	v_add_u32_e32 v3, v5, v3
	v_lshrrev_b32_e32 v2, 22, v2
	v_lshlrev_b32_e32 v4, 1, v3
	v_lshrrev_b32_e32 v7, 2, v3
	v_and_b32_e32 v5, 3, v5
	s_mov_b32 s0, 0x7fffe0
	v_add_u32_e32 v2, v1, v2
	v_and_b32_e32 v4, 24, v4
	v_and_b32_e32 v7, 4, v7
	v_and_or_b32 v5, v3, s0, v5
	v_ashrrev_i32_e32 v2, 10, v2
	v_or3_b32 v5, v5, v7, v4
	v_lshl_add_u32 v4, v3, 9, v0
	v_mul_i32_i24_e32 v3, 0x400, v2
	v_sub_u32_e32 v1, v1, v3
	v_lshrrev_b32_e32 v3, 4, v1
	v_bitop3_b32 v1, v3, v1, 32 bitop3:0x6c
	v_lshl_add_u32 v0, v5, 9, v0
	v_ashrrev_i32_e32 v5, 31, v1
	v_lshrrev_b32_e32 v5, 26, v5
	v_add_u32_e32 v5, v1, v5
	v_lshlrev_b32_e32 v3, 3, v2
	v_ashrrev_i32_e32 v7, 6, v5
	v_and_b32_e32 v5, 0xc0, v5
	v_and_b32_e32 v3, -16, v3
	v_sub_u32_e32 v1, v1, v5
	v_add_u32_e32 v3, v7, v3
	v_lshlrev_b32_e32 v2, 5, v2
	v_ashrrev_i16_sdwa v1, v6, sext(v1) dst_sel:DWORD dst_unused:UNUSED_PAD src0_sel:DWORD src1_sel:BYTE_0
	v_and_b32_e32 v2, 32, v2
	v_bfe_i32 v1, v1, 0, 16
	v_lshlrev_b32_e32 v5, 1, v3
	v_lshrrev_b32_e32 v6, 2, v3
	v_and_b32_e32 v7, 3, v7
	v_and_b32_e32 v5, 24, v5
	v_and_b32_e32 v6, 4, v6
	v_and_or_b32 v7, v3, s0, v7
	v_add_lshl_u32 v1, v2, v1, 1
	v_or3_b32 v5, v7, v6, v5
	v_lshl_add_u32 v6, v3, 9, v1
	v_lshl_add_u32 v2, v5, 9, v1
	s_add_u32 s10, s18, 0x10100
	ds_read_b128 v[8:11], v141
	ds_read_b128 v[12:15], v141 offset:1024
	ds_read_b128 v[16:19], v141 offset:2048
	ds_read_b128 v[20:23], v141 offset:3072
	ds_read_b128 v[24:27], v140
	ds_read_b128 v[28:31], v140 offset:1024
	ds_read_b128 v[32:35], v140 offset:2048
	ds_read_b128 v[36:39], v140 offset:3072
	s_addc_u32 s11, s19, 0
	s_add_u32 s8, s14, 0x10100
	s_addc_u32 s9, s15, 0
	s_add_u32 s0, s18, 0x10180
	s_addc_u32 s1, s19, 0
	s_add_u32 s24, s14, 0x10080
	s_mov_b32 m0, s51
	s_addc_u32 s25, s15, 0
	ds_read_b128 v[40:43], v137
	ds_read_b128 v[44:47], v137 offset:1024
	ds_read_b128 v[48:51], v137 offset:2048
	ds_read_b128 v[52:55], v137 offset:3072
	ds_read_b128 v[56:59], v137 offset:4096
	ds_read_b128 v[60:63], v137 offset:5120
	ds_read_b128 v[64:67], v137 offset:6144
	ds_read_b128 v[68:71], v137 offset:7168
	global_load_lds_dwordx4 v4, s[24:25]
	s_mov_b32 m0, s50
	v_mov_b32_e32 v5, 0
	global_load_lds_dwordx4 v6, s[24:25]
	s_waitcnt vmcnt(8)
	s_waitcnt lgkmcnt(0)
	v_mov_b32_e32 v7, v5
	s_barrier
	s_setprio 1
	v_mfma_f32_16x16x32_bf16 v[72:75], v[8:11], v[40:43], 0
	v_mfma_f32_16x16x32_bf16 v[76:79], v[16:19], v[40:43], 0
	v_mfma_f32_16x16x32_bf16 v[80:83], v[8:11], v[48:51], 0
	v_mfma_f32_16x16x32_bf16 v[84:87], v[16:19], v[48:51], 0
	v_mfma_f32_16x16x32_bf16 v[88:91], v[8:11], v[56:59], 0
	v_mfma_f32_16x16x32_bf16 v[92:95], v[16:19], v[56:59], 0
	v_mfma_f32_16x16x32_bf16 v[96:99], v[8:11], v[64:67], 0
	v_mfma_f32_16x16x32_bf16 v[100:103], v[16:19], v[64:67], 0
	v_mfma_f32_16x16x32_bf16 v[72:75], v[12:15], v[44:47], v[72:75]
	v_mfma_f32_16x16x32_bf16 v[76:79], v[20:23], v[44:47], v[76:79]
	v_mfma_f32_16x16x32_bf16 v[80:83], v[12:15], v[52:55], v[80:83]
	v_mfma_f32_16x16x32_bf16 v[84:87], v[20:23], v[52:55], v[84:87]
	v_mfma_f32_16x16x32_bf16 v[88:91], v[12:15], v[60:63], v[88:91]
	v_mfma_f32_16x16x32_bf16 v[92:95], v[20:23], v[60:63], v[92:95]
	v_mfma_f32_16x16x32_bf16 v[96:99], v[12:15], v[68:71], v[96:99]
	v_mfma_f32_16x16x32_bf16 v[100:103], v[20:23], v[68:71], v[100:103]
	v_mfma_f32_16x16x32_bf16 v[104:107], v[24:27], v[40:43], 0
	v_mfma_f32_16x16x32_bf16 v[40:43], v[32:35], v[40:43], 0
	v_mfma_f32_16x16x32_bf16 v[104:107], v[28:31], v[44:47], v[104:107]
	v_mfma_f32_16x16x32_bf16 v[40:43], v[36:39], v[44:47], v[40:43]
	v_mfma_f32_16x16x32_bf16 v[44:47], v[24:27], v[48:51], 0
	v_mfma_f32_16x16x32_bf16 v[48:51], v[32:35], v[48:51], 0
	v_mfma_f32_16x16x32_bf16 v[44:47], v[28:31], v[52:55], v[44:47]
	v_mfma_f32_16x16x32_bf16 v[48:51], v[36:39], v[52:55], v[48:51]
	v_mfma_f32_16x16x32_bf16 v[52:55], v[24:27], v[56:59], 0
	v_mfma_f32_16x16x32_bf16 v[56:59], v[32:35], v[56:59], 0
	v_mfma_f32_16x16x32_bf16 v[52:55], v[28:31], v[60:63], v[52:55]
	v_mfma_f32_16x16x32_bf16 v[56:59], v[36:39], v[60:63], v[56:59]
	v_mfma_f32_16x16x32_bf16 v[60:63], v[24:27], v[64:67], 0
	v_mfma_f32_16x16x32_bf16 v[64:67], v[32:35], v[64:67], 0
	v_mfma_f32_16x16x32_bf16 v[60:63], v[28:31], v[68:71], v[60:63]
	v_mfma_f32_16x16x32_bf16 v[64:67], v[36:39], v[68:71], v[64:67]
	s_setprio 0
	s_barrier
	v_mov_b32_e32 v1, v5
	v_lshl_add_u64 v[134:135], s[18:19], 0, v[0:1]
	s_mov_b64 s[24:25], 0x100
	v_mov_b32_e32 v3, v5
	s_mov_b32 m0, s49
	v_lshl_add_u64 v[146:147], v[134:135], 0, s[24:25]
	v_lshl_add_u64 v[210:211], s[18:19], 0, v[2:3]
	ds_read_b128 v[68:71], v137 offset:16384
	ds_read_b128 v[108:111], v137 offset:17408
	ds_read_b128 v[112:115], v137 offset:18432
	ds_read_b128 v[116:119], v137 offset:19456
	ds_read_b128 v[120:123], v137 offset:20480
	ds_read_b128 v[124:127], v137 offset:21504
	ds_read_b128 v[130:133], v137 offset:22528
	ds_read_b128 v[142:145], v137 offset:23552
	global_load_lds_dwordx4 v[146:147], off
	v_lshl_add_u64 v[146:147], v[210:211], 0, s[24:25]
	s_mov_b32 m0, s47
	v_lshl_add_u64 v[212:213], s[14:15], 0, v[4:5]
	global_load_lds_dwordx4 v[146:147], off
	s_mov_b32 m0, s48
	v_lshl_add_u64 v[146:147], v[212:213], 0, s[24:25]
	global_load_lds_dwordx4 v0, s[10:11]
	s_mov_b32 m0, s46
	v_lshl_add_u64 v[214:215], s[14:15], 0, v[6:7]
	global_load_lds_dwordx4 v2, s[10:11]
	s_mov_b32 m0, s40
	s_nop 0
	global_load_lds_dwordx4 v[146:147], off
	v_lshl_add_u64 v[146:147], v[214:215], 0, s[24:25]
	s_mov_b32 m0, s45
	s_nop 0
	global_load_lds_dwordx4 v[146:147], off
	s_waitcnt vmcnt(8)
	s_waitcnt lgkmcnt(0)
	s_barrier
	s_setprio 1
	v_mfma_f32_16x16x32_bf16 v[146:149], v[8:11], v[68:71], 0
	v_mfma_f32_16x16x32_bf16 v[154:157], v[8:11], v[112:115], 0
	v_mfma_f32_16x16x32_bf16 v[162:165], v[8:11], v[120:123], 0
	v_mfma_f32_16x16x32_bf16 v[8:11], v[8:11], v[130:133], 0
	v_mfma_f32_16x16x32_bf16 v[146:149], v[12:15], v[108:111], v[146:149]
	v_mfma_f32_16x16x32_bf16 v[154:157], v[12:15], v[116:119], v[154:157]
	v_mfma_f32_16x16x32_bf16 v[162:165], v[12:15], v[124:127], v[162:165]
	v_mfma_f32_16x16x32_bf16 v[8:11], v[12:15], v[142:145], v[8:11]
	v_mfma_f32_16x16x32_bf16 v[12:15], v[16:19], v[130:133], 0
	v_mfma_f32_16x16x32_bf16 v[150:153], v[16:19], v[68:71], 0
	v_mfma_f32_16x16x32_bf16 v[158:161], v[16:19], v[112:115], 0
	v_mfma_f32_16x16x32_bf16 v[166:169], v[16:19], v[120:123], 0
	v_mfma_f32_16x16x32_bf16 v[12:15], v[20:23], v[142:145], v[12:15]
	v_mfma_f32_16x16x32_bf16 v[150:153], v[20:23], v[108:111], v[150:153]
	v_mfma_f32_16x16x32_bf16 v[158:161], v[20:23], v[116:119], v[158:161]
	v_mfma_f32_16x16x32_bf16 v[166:169], v[20:23], v[124:127], v[166:169]
	v_mfma_f32_16x16x32_bf16 v[16:19], v[24:27], v[68:71], 0
	v_mfma_f32_16x16x32_bf16 v[20:23], v[32:35], v[68:71], 0
	v_mfma_f32_16x16x32_bf16 v[16:19], v[28:31], v[108:111], v[16:19]
	v_mfma_f32_16x16x32_bf16 v[20:23], v[36:39], v[108:111], v[20:23]
	v_mfma_f32_16x16x32_bf16 v[68:71], v[24:27], v[112:115], 0
	v_mfma_f32_16x16x32_bf16 v[108:111], v[32:35], v[112:115], 0
	v_mfma_f32_16x16x32_bf16 v[112:115], v[24:27], v[120:123], 0
	v_mfma_f32_16x16x32_bf16 v[24:27], v[24:27], v[130:133], 0
	v_mfma_f32_16x16x32_bf16 v[68:71], v[28:31], v[116:119], v[68:71]
	v_mfma_f32_16x16x32_bf16 v[108:111], v[36:39], v[116:119], v[108:111]
	v_mfma_f32_16x16x32_bf16 v[112:115], v[28:31], v[124:127], v[112:115]
	v_mfma_f32_16x16x32_bf16 v[116:119], v[32:35], v[120:123], 0
	v_mfma_f32_16x16x32_bf16 v[24:27], v[28:31], v[142:145], v[24:27]
	v_mfma_f32_16x16x32_bf16 v[28:31], v[32:35], v[130:133], 0
	v_mfma_f32_16x16x32_bf16 v[116:119], v[36:39], v[124:127], v[116:119]
	v_mfma_f32_16x16x32_bf16 v[28:31], v[36:39], v[142:145], v[28:31]
	s_setprio 0
	s_barrier
	ds_read_b128 v[32:35], v139
	ds_read_b128 v[36:39], v139 offset:1024
	ds_read_b128 v[120:123], v139 offset:2048
	ds_read_b128 v[124:127], v139 offset:3072
	ds_read_b128 v[130:133], v138
	ds_read_b128 v[142:145], v138 offset:1024
	ds_read_b128 v[170:173], v138 offset:2048
	ds_read_b128 v[174:177], v138 offset:3072
	s_mov_b32 m0, s34
	ds_read_b128 v[178:181], v137 offset:32768
	ds_read_b128 v[182:185], v137 offset:33792
	ds_read_b128 v[186:189], v137 offset:34816
	ds_read_b128 v[190:193], v137 offset:35840
	ds_read_b128 v[194:197], v137 offset:36864
	ds_read_b128 v[198:201], v137 offset:37888
	ds_read_b128 v[202:205], v137 offset:38912
	ds_read_b128 v[206:209], v137 offset:39936
	global_load_lds_dwordx4 v4, s[8:9]
	s_mov_b32 m0, s35
	s_nop 0
	global_load_lds_dwordx4 v6, s[8:9]
	s_waitcnt vmcnt(8)
	s_waitcnt lgkmcnt(0)
	s_barrier
	s_setprio 1
	v_mfma_f32_16x16x32_bf16 v[72:75], v[32:35], v[178:181], v[72:75]
	v_mfma_f32_16x16x32_bf16 v[76:79], v[120:123], v[178:181], v[76:79]
	v_mfma_f32_16x16x32_bf16 v[80:83], v[32:35], v[186:189], v[80:83]
	v_mfma_f32_16x16x32_bf16 v[84:87], v[120:123], v[186:189], v[84:87]
	v_mfma_f32_16x16x32_bf16 v[88:91], v[32:35], v[194:197], v[88:91]
	v_mfma_f32_16x16x32_bf16 v[92:95], v[120:123], v[194:197], v[92:95]
	v_mfma_f32_16x16x32_bf16 v[96:99], v[32:35], v[202:205], v[96:99]
	v_mfma_f32_16x16x32_bf16 v[100:103], v[120:123], v[202:205], v[100:103]
	v_mfma_f32_16x16x32_bf16 v[72:75], v[36:39], v[182:185], v[72:75]
	v_mfma_f32_16x16x32_bf16 v[76:79], v[124:127], v[182:185], v[76:79]
	v_mfma_f32_16x16x32_bf16 v[80:83], v[36:39], v[190:193], v[80:83]
	v_mfma_f32_16x16x32_bf16 v[84:87], v[124:127], v[190:193], v[84:87]
	v_mfma_f32_16x16x32_bf16 v[88:91], v[36:39], v[198:201], v[88:91]
	v_mfma_f32_16x16x32_bf16 v[92:95], v[124:127], v[198:201], v[92:95]
	v_mfma_f32_16x16x32_bf16 v[96:99], v[36:39], v[206:209], v[96:99]
	v_mfma_f32_16x16x32_bf16 v[100:103], v[124:127], v[206:209], v[100:103]
	v_mfma_f32_16x16x32_bf16 v[104:107], v[130:133], v[178:181], v[104:107]
	v_mfma_f32_16x16x32_bf16 v[40:43], v[170:173], v[178:181], v[40:43]
	v_mfma_f32_16x16x32_bf16 v[44:47], v[130:133], v[186:189], v[44:47]
	v_mfma_f32_16x16x32_bf16 v[48:51], v[170:173], v[186:189], v[48:51]
	v_mfma_f32_16x16x32_bf16 v[52:55], v[130:133], v[194:197], v[52:55]
	v_mfma_f32_16x16x32_bf16 v[56:59], v[170:173], v[194:197], v[56:59]
	v_mfma_f32_16x16x32_bf16 v[60:63], v[130:133], v[202:205], v[60:63]
	v_mfma_f32_16x16x32_bf16 v[64:67], v[170:173], v[202:205], v[64:67]
	v_mfma_f32_16x16x32_bf16 v[104:107], v[142:145], v[182:185], v[104:107]
	v_mfma_f32_16x16x32_bf16 v[40:43], v[174:177], v[182:185], v[40:43]
	v_mfma_f32_16x16x32_bf16 v[44:47], v[142:145], v[190:193], v[44:47]
	v_mfma_f32_16x16x32_bf16 v[48:51], v[174:177], v[190:193], v[48:51]
	v_mfma_f32_16x16x32_bf16 v[52:55], v[142:145], v[198:201], v[52:55]
	v_mfma_f32_16x16x32_bf16 v[56:59], v[174:177], v[198:201], v[56:59]
	v_mfma_f32_16x16x32_bf16 v[60:63], v[142:145], v[206:209], v[60:63]
	v_mfma_f32_16x16x32_bf16 v[64:67], v[174:177], v[206:209], v[64:67]
	s_setprio 0
	s_barrier
	s_mov_b64 s[8:9], 0x180
	s_mov_b32 m0, s44
	v_lshl_add_u64 v[134:135], v[134:135], 0, s[8:9]
	ds_read_b128 v[178:181], v137 offset:49152
	ds_read_b128 v[182:185], v137 offset:50176
	ds_read_b128 v[186:189], v137 offset:51200
	ds_read_b128 v[190:193], v137 offset:52224
	ds_read_b128 v[194:197], v137 offset:53248
	ds_read_b128 v[198:201], v137 offset:54272
	ds_read_b128 v[202:205], v137 offset:55296
	ds_read_b128 v[206:209], v137 offset:56320
	global_load_lds_dwordx4 v[134:135], off
	v_lshl_add_u64 v[134:135], v[210:211], 0, s[8:9]
	s_mov_b32 m0, s42
	s_nop 0
	global_load_lds_dwordx4 v[134:135], off
	s_mov_b32 m0, s43
	v_lshl_add_u64 v[134:135], v[212:213], 0, s[8:9]
	global_load_lds_dwordx4 v0, s[0:1]
	s_mov_b32 m0, s41
	s_nop 0
	global_load_lds_dwordx4 v2, s[0:1]
	s_mov_b32 m0, s13
	s_nop 0
	global_load_lds_dwordx4 v[134:135], off
	v_lshl_add_u64 v[134:135], v[214:215], 0, s[8:9]
	s_mov_b32 m0, s33
	s_nop 0
	global_load_lds_dwordx4 v[134:135], off
	s_waitcnt vmcnt(8)
	s_waitcnt lgkmcnt(0)
	s_barrier
	s_setprio 1
	v_mfma_f32_16x16x32_bf16 v[8:11], v[32:35], v[202:205], v[8:11]
	v_mfma_f32_16x16x32_bf16 v[12:15], v[120:123], v[202:205], v[12:15]
	v_mfma_f32_16x16x32_bf16 v[146:149], v[32:35], v[178:181], v[146:149]
	v_mfma_f32_16x16x32_bf16 v[150:153], v[120:123], v[178:181], v[150:153]
	v_mfma_f32_16x16x32_bf16 v[154:157], v[32:35], v[186:189], v[154:157]
	v_mfma_f32_16x16x32_bf16 v[158:161], v[120:123], v[186:189], v[158:161]
	v_mfma_f32_16x16x32_bf16 v[162:165], v[32:35], v[194:197], v[162:165]
	v_mfma_f32_16x16x32_bf16 v[166:169], v[120:123], v[194:197], v[166:169]
	v_mfma_f32_16x16x32_bf16 v[8:11], v[36:39], v[206:209], v[8:11]
	v_mfma_f32_16x16x32_bf16 v[12:15], v[124:127], v[206:209], v[12:15]
	v_mfma_f32_16x16x32_bf16 v[146:149], v[36:39], v[182:185], v[146:149]
	v_mfma_f32_16x16x32_bf16 v[150:153], v[124:127], v[182:185], v[150:153]
	v_mfma_f32_16x16x32_bf16 v[154:157], v[36:39], v[190:193], v[154:157]
	v_mfma_f32_16x16x32_bf16 v[158:161], v[124:127], v[190:193], v[158:161]
	v_mfma_f32_16x16x32_bf16 v[162:165], v[36:39], v[198:201], v[162:165]
	v_mfma_f32_16x16x32_bf16 v[166:169], v[124:127], v[198:201], v[166:169]
	v_mfma_f32_16x16x32_bf16 v[16:19], v[130:133], v[178:181], v[16:19]
	v_mfma_f32_16x16x32_bf16 v[20:23], v[170:173], v[178:181], v[20:23]
	v_mfma_f32_16x16x32_bf16 v[32:35], v[130:133], v[186:189], v[68:71]
	v_mfma_f32_16x16x32_bf16 v[36:39], v[170:173], v[186:189], v[108:111]
	v_mfma_f32_16x16x32_bf16 v[68:71], v[130:133], v[194:197], v[112:115]
	v_mfma_f32_16x16x32_bf16 v[108:111], v[170:173], v[194:197], v[116:119]
	v_mfma_f32_16x16x32_bf16 v[24:27], v[130:133], v[202:205], v[24:27]
	v_mfma_f32_16x16x32_bf16 v[28:31], v[170:173], v[202:205], v[28:31]
	v_mfma_f32_16x16x32_bf16 v[16:19], v[142:145], v[182:185], v[16:19]
	v_mfma_f32_16x16x32_bf16 v[20:23], v[174:177], v[182:185], v[20:23]
	v_mfma_f32_16x16x32_bf16 v[32:35], v[142:145], v[190:193], v[32:35]
	v_mfma_f32_16x16x32_bf16 v[36:39], v[174:177], v[190:193], v[36:39]
	v_mfma_f32_16x16x32_bf16 v[68:71], v[142:145], v[198:201], v[68:71]
	v_mfma_f32_16x16x32_bf16 v[108:111], v[174:177], v[198:201], v[108:111]
	v_mfma_f32_16x16x32_bf16 v[24:27], v[142:145], v[206:209], v[24:27]
	v_mfma_f32_16x16x32_bf16 v[28:31], v[174:177], v[206:209], v[28:31]
	s_setprio 0
	s_barrier
	s_nop 0
	ds_read_b128 v[112:115], v141
	ds_read_b128 v[116:119], v141 offset:1024
	ds_read_b128 v[120:123], v141 offset:2048
	ds_read_b128 v[124:127], v141 offset:3072
	ds_read_b128 v[130:133], v140
	ds_read_b128 v[142:145], v140 offset:1024
	ds_read_b128 v[170:173], v140 offset:2048
	ds_read_b128 v[174:177], v140 offset:3072
	s_add_u32 s0, s14, 0x10180
	s_mov_b32 m0, s51
	s_addc_u32 s1, s15, 0
	ds_read_b128 v[178:181], v137
	ds_read_b128 v[182:185], v137 offset:1024
	ds_read_b128 v[186:189], v137 offset:2048
	ds_read_b128 v[190:193], v137 offset:3072
	ds_read_b128 v[194:197], v137 offset:4096
	ds_read_b128 v[198:201], v137 offset:5120
	ds_read_b128 v[202:205], v137 offset:6144
	ds_read_b128 v[206:209], v137 offset:7168
	global_load_lds_dwordx4 v4, s[0:1]
	s_mov_b32 m0, s50
	s_nop 0
	global_load_lds_dwordx4 v6, s[0:1]
	s_waitcnt vmcnt(8)
	s_waitcnt lgkmcnt(0)
	s_barrier
	s_setprio 1
	v_mfma_f32_16x16x32_bf16 v[96:99], v[112:115], v[202:205], v[96:99]
	v_mfma_f32_16x16x32_bf16 v[72:75], v[112:115], v[178:181], v[72:75]
	v_mfma_f32_16x16x32_bf16 v[76:79], v[120:123], v[178:181], v[76:79]
	v_mfma_f32_16x16x32_bf16 v[80:83], v[112:115], v[186:189], v[80:83]
	v_mfma_f32_16x16x32_bf16 v[84:87], v[120:123], v[186:189], v[84:87]
	v_mfma_f32_16x16x32_bf16 v[88:91], v[112:115], v[194:197], v[88:91]
	v_mfma_f32_16x16x32_bf16 v[92:95], v[120:123], v[194:197], v[92:95]
	v_mfma_f32_16x16x32_bf16 v[210:213], v[116:119], v[206:209], v[96:99]
	v_mfma_f32_16x16x32_bf16 v[96:99], v[120:123], v[202:205], v[100:103]
	v_mfma_f32_16x16x32_bf16 v[72:75], v[116:119], v[182:185], v[72:75]
	v_mfma_f32_16x16x32_bf16 v[76:79], v[124:127], v[182:185], v[76:79]
	v_mfma_f32_16x16x32_bf16 v[80:83], v[116:119], v[190:193], v[80:83]
	v_mfma_f32_16x16x32_bf16 v[84:87], v[124:127], v[190:193], v[84:87]
	v_mfma_f32_16x16x32_bf16 v[88:91], v[116:119], v[198:201], v[88:91]
	v_mfma_f32_16x16x32_bf16 v[92:95], v[124:127], v[198:201], v[92:95]
	v_mfma_f32_16x16x32_bf16 v[100:103], v[124:127], v[206:209], v[96:99]
	v_mfma_f32_16x16x32_bf16 v[48:51], v[170:173], v[186:189], v[48:51]
	v_mfma_f32_16x16x32_bf16 v[96:99], v[130:133], v[178:181], v[104:107]
	v_mfma_f32_16x16x32_bf16 v[40:43], v[170:173], v[178:181], v[40:43]
	v_mfma_f32_16x16x32_bf16 v[178:181], v[174:177], v[190:193], v[48:51]
	v_mfma_f32_16x16x32_bf16 v[48:51], v[130:133], v[194:197], v[52:55]
	v_mfma_f32_16x16x32_bf16 v[52:55], v[142:145], v[198:201], v[48:51]
	v_mfma_f32_16x16x32_bf16 v[48:51], v[170:173], v[194:197], v[56:59]
	v_mfma_f32_16x16x32_bf16 v[214:217], v[142:145], v[182:185], v[96:99]
	v_mfma_f32_16x16x32_bf16 v[40:43], v[174:177], v[182:185], v[40:43]
	v_mfma_f32_16x16x32_bf16 v[182:185], v[174:177], v[198:201], v[48:51]
	v_mfma_f32_16x16x32_bf16 v[48:51], v[130:133], v[202:205], v[60:63]
	v_mfma_f32_16x16x32_bf16 v[44:47], v[130:133], v[186:189], v[44:47]
	v_mfma_f32_16x16x32_bf16 v[60:63], v[142:145], v[206:209], v[48:51]
	v_mfma_f32_16x16x32_bf16 v[48:51], v[170:173], v[202:205], v[64:67]
	v_mfma_f32_16x16x32_bf16 v[44:47], v[142:145], v[190:193], v[44:47]
	v_mfma_f32_16x16x32_bf16 v[64:67], v[174:177], v[206:209], v[48:51]
	s_setprio 0
	s_barrier
	s_mov_b32 m0, s49
	s_nop 2
	ds_read_b128 v[48:51], v137 offset:16384
	ds_read_b128 v[56:59], v137 offset:17408
	ds_read_b128 v[96:99], v137 offset:18432
	ds_read_b128 v[104:107], v137 offset:19456
	ds_read_b128 v[186:189], v137 offset:20480
	ds_read_b128 v[190:193], v137 offset:21504
	ds_read_b128 v[194:197], v137 offset:22528
	ds_read_b128 v[198:201], v137 offset:23552
	global_load_lds_dwordx4 v0, s[18:19]
	s_mov_b32 m0, s47
	v_lshl_add_u64 v[134:135], s[18:19], 0, v[0:1]
	global_load_lds_dwordx4 v2, s[18:19]
	s_mov_b32 m0, s48
	v_lshl_add_u64 v[246:247], s[18:19], 0, v[2:3]
	global_load_lds_dwordx4 v0, s[16:17]
	s_mov_b32 m0, s46
	v_lshl_add_u64 v[248:249], s[14:15], 0, v[4:5]
	global_load_lds_dwordx4 v2, s[16:17]
	s_mov_b32 m0, s40
	v_lshl_add_u64 v[250:251], s[14:15], 0, v[6:7]
	global_load_lds_dwordx4 v4, s[14:15]
	s_mov_b32 m0, s45
	s_nop 0
	global_load_lds_dwordx4 v6, s[14:15]
	s_waitcnt vmcnt(8)
	s_waitcnt lgkmcnt(0)
	s_barrier
	s_setprio 1
	v_mfma_f32_16x16x32_bf16 v[8:11], v[112:115], v[194:197], v[8:11]
	v_mfma_f32_16x16x32_bf16 v[146:149], v[112:115], v[48:51], v[146:149]
	v_mfma_f32_16x16x32_bf16 v[150:153], v[120:123], v[48:51], v[150:153]
	v_mfma_f32_16x16x32_bf16 v[154:157], v[112:115], v[96:99], v[154:157]
	v_mfma_f32_16x16x32_bf16 v[158:161], v[120:123], v[96:99], v[158:161]
	v_mfma_f32_16x16x32_bf16 v[162:165], v[112:115], v[186:189], v[162:165]
	v_mfma_f32_16x16x32_bf16 v[166:169], v[120:123], v[186:189], v[166:169]
	v_mfma_f32_16x16x32_bf16 v[8:11], v[116:119], v[198:201], v[8:11]
	v_mfma_f32_16x16x32_bf16 v[12:15], v[120:123], v[194:197], v[12:15]
	v_mfma_f32_16x16x32_bf16 v[146:149], v[116:119], v[56:59], v[146:149]
	v_mfma_f32_16x16x32_bf16 v[150:153], v[124:127], v[56:59], v[150:153]
	v_mfma_f32_16x16x32_bf16 v[154:157], v[116:119], v[104:107], v[154:157]
	v_mfma_f32_16x16x32_bf16 v[158:161], v[124:127], v[104:107], v[158:161]
	v_mfma_f32_16x16x32_bf16 v[162:165], v[116:119], v[190:193], v[162:165]
	v_mfma_f32_16x16x32_bf16 v[166:169], v[124:127], v[190:193], v[166:169]
	v_mfma_f32_16x16x32_bf16 v[202:205], v[124:127], v[198:201], v[12:15]
	v_mfma_f32_16x16x32_bf16 v[12:15], v[130:133], v[48:51], v[16:19]
	v_mfma_f32_16x16x32_bf16 v[16:19], v[142:145], v[56:59], v[12:15]
	v_mfma_f32_16x16x32_bf16 v[12:15], v[170:173], v[48:51], v[20:23]
	v_mfma_f32_16x16x32_bf16 v[206:209], v[174:177], v[56:59], v[12:15]
	v_mfma_f32_16x16x32_bf16 v[12:15], v[130:133], v[96:99], v[32:35]
	v_mfma_f32_16x16x32_bf16 v[32:35], v[142:145], v[104:107], v[12:15]
	v_mfma_f32_16x16x32_bf16 v[12:15], v[170:173], v[96:99], v[36:39]
	v_mfma_f32_16x16x32_bf16 v[218:221], v[174:177], v[104:107], v[12:15]
	v_mfma_f32_16x16x32_bf16 v[12:15], v[130:133], v[186:189], v[68:71]
	v_mfma_f32_16x16x32_bf16 v[222:225], v[142:145], v[190:193], v[12:15]
	v_mfma_f32_16x16x32_bf16 v[12:15], v[170:173], v[186:189], v[108:111]
	v_mfma_f32_16x16x32_bf16 v[186:189], v[174:177], v[190:193], v[12:15]
	v_mfma_f32_16x16x32_bf16 v[12:15], v[130:133], v[194:197], v[24:27]
	v_mfma_f32_16x16x32_bf16 v[130:133], v[142:145], v[198:201], v[12:15]
	v_mfma_f32_16x16x32_bf16 v[12:15], v[170:173], v[194:197], v[28:31]
	v_mfma_f32_16x16x32_bf16 v[140:143], v[174:177], v[198:201], v[12:15]
	s_setprio 0
	s_barrier
	s_nop 4
	ds_read_b128 v[12:15], v139
	ds_read_b128 v[24:27], v139 offset:1024
	ds_read_b128 v[170:173], v139 offset:2048
	ds_read_b128 v[174:177], v139 offset:3072
	ds_read_b128 v[190:193], v138
	ds_read_b128 v[194:197], v138 offset:1024
	ds_read_b128 v[198:201], v138 offset:2048
	ds_read_b128 v[226:229], v138 offset:3072
	s_mov_b32 m0, s34
	ds_read_b128 v[20:23], v137 offset:32768
	ds_read_b128 v[28:31], v137 offset:33792
	ds_read_b128 v[36:39], v137 offset:34816
	ds_read_b128 v[68:71], v137 offset:35840
	ds_read_b128 v[230:233], v137 offset:36864
	ds_read_b128 v[234:237], v137 offset:37888
	ds_read_b128 v[238:241], v137 offset:38912
	ds_read_b128 v[242:245], v137 offset:39936
	global_load_lds_dwordx4 v4, s[20:21]
	s_mov_b32 m0, s35
	s_nop 0
	global_load_lds_dwordx4 v6, s[20:21]
	s_waitcnt vmcnt(8)
	s_waitcnt lgkmcnt(0)
	s_barrier
; #define PG8_BAR __builtin_amdgcn_s_barrier()
; template <int ROT, class Epi0, class Epi1, class Late, class Post0>
; __device__ __forceinline__ void gemm_phase_pair(PG8_LAS unsigned char* lds, const Gemm g0, const Gemm g1, const Unit u, const Epi0& E0, const Epi1& E1, int wid_in, const Late& late, const Post0& post0) {
;     ...
;     if (wr == 0) PG8_BAR;
	s_setprio 1
	v_mfma_f32_16x16x32_bf16 v[4:7], v[12:15], v[20:23], v[72:75]
	v_mfma_f32_16x16x32_bf16 v[120:123], v[24:27], v[28:31], v[4:7]
	v_mfma_f32_16x16x32_bf16 v[4:7], v[170:173], v[20:23], v[76:79]
	v_mfma_f32_16x16x32_bf16 v[112:115], v[174:177], v[28:31], v[4:7]
	v_mfma_f32_16x16x32_bf16 v[4:7], v[12:15], v[36:39], v[80:83]
	v_mfma_f32_16x16x32_bf16 v[104:107], v[24:27], v[68:71], v[4:7]
	v_mfma_f32_16x16x32_bf16 v[4:7], v[170:173], v[36:39], v[84:87]
	v_mfma_f32_16x16x32_bf16 v[96:99], v[174:177], v[68:71], v[4:7]
	v_mfma_f32_16x16x32_bf16 v[4:7], v[12:15], v[230:233], v[88:91]
	v_mfma_f32_16x16x32_bf16 v[88:91], v[24:27], v[234:237], v[4:7]
	v_mfma_f32_16x16x32_bf16 v[4:7], v[170:173], v[230:233], v[92:95]
	v_mfma_f32_16x16x32_bf16 v[80:83], v[174:177], v[234:237], v[4:7]
	v_mfma_f32_16x16x32_bf16 v[4:7], v[12:15], v[238:241], v[210:213]
	v_mfma_f32_16x16x32_bf16 v[56:59], v[24:27], v[242:245], v[4:7]
	v_mfma_f32_16x16x32_bf16 v[4:7], v[170:173], v[238:241], v[100:103]
	v_mfma_f32_16x16x32_bf16 v[48:51], v[174:177], v[242:245], v[4:7]
	v_mfma_f32_16x16x32_bf16 v[4:7], v[190:193], v[20:23], v[214:217]
	v_mfma_f32_16x16x32_bf16 v[124:127], v[194:197], v[28:31], v[4:7]
	v_mfma_f32_16x16x32_bf16 v[4:7], v[198:201], v[20:23], v[40:43]
	v_mfma_f32_16x16x32_bf16 v[116:119], v[226:229], v[28:31], v[4:7]
	v_mfma_f32_16x16x32_bf16 v[4:7], v[190:193], v[36:39], v[44:47]
	v_mfma_f32_16x16x32_bf16 v[108:111], v[194:197], v[68:71], v[4:7]
	v_mfma_f32_16x16x32_bf16 v[4:7], v[198:201], v[36:39], v[178:181]
	v_mfma_f32_16x16x32_bf16 v[100:103], v[226:229], v[68:71], v[4:7]
	v_mfma_f32_16x16x32_bf16 v[4:7], v[190:193], v[230:233], v[52:55]
	v_mfma_f32_16x16x32_bf16 v[92:95], v[194:197], v[234:237], v[4:7]
	v_mfma_f32_16x16x32_bf16 v[4:7], v[198:201], v[230:233], v[182:185]
	v_mfma_f32_16x16x32_bf16 v[84:87], v[226:229], v[234:237], v[4:7]
	v_mfma_f32_16x16x32_bf16 v[4:7], v[190:193], v[238:241], v[60:63]
	v_mfma_f32_16x16x32_bf16 v[60:63], v[194:197], v[242:245], v[4:7]
	v_mfma_f32_16x16x32_bf16 v[4:7], v[198:201], v[238:241], v[64:67]
	v_mfma_f32_16x16x32_bf16 v[52:55], v[226:229], v[242:245], v[4:7]
	s_setprio 0
	s_barrier
	s_mov_b64 s[0:1], 0x80
	s_mov_b32 m0, s44
	s_nop 2
	v_lshl_add_u64 v[4:5], v[134:135], 0, s[0:1]
	ds_read_b128 v[40:43], v137 offset:49152
	ds_read_b128 v[64:67], v137 offset:50176
	ds_read_b128 v[178:181], v137 offset:51200
	ds_read_b128 v[182:185], v137 offset:52224
	ds_read_b128 v[210:213], v137 offset:53248
	ds_read_b128 v[214:217], v137 offset:54272
	ds_read_b128 v[230:233], v137 offset:55296
	ds_read_b128 v[234:237], v137 offset:56320
	global_load_lds_dwordx4 v[4:5], off
	v_lshl_add_u64 v[4:5], v[246:247], 0, s[0:1]
	s_mov_b32 m0, s42
	s_nop 0
	global_load_lds_dwordx4 v[4:5], off
	s_mov_b32 m0, s43
	s_nop 0
	global_load_lds_dwordx4 v0, s[22:23]
	s_mov_b32 m0, s41
	v_lshl_add_u64 v[0:1], v[248:249], 0, s[0:1]
	global_load_lds_dwordx4 v2, s[22:23]
	s_mov_b32 m0, s13
	s_nop 0
	global_load_lds_dwordx4 v[0:1], off
	v_lshl_add_u64 v[0:1], v[250:251], 0, s[0:1]
	s_mov_b32 m0, s33
	s_nop 0
	global_load_lds_dwordx4 v[0:1], off
	s_waitcnt vmcnt(8)
	s_waitcnt lgkmcnt(0)
	s_barrier
	s_setprio 1
	v_mfma_f32_16x16x32_bf16 v[0:3], v[12:15], v[40:43], v[146:149]
	v_mfma_f32_16x16x32_bf16 v[76:79], v[24:27], v[64:67], v[0:3]
	v_mfma_f32_16x16x32_bf16 v[0:3], v[170:173], v[40:43], v[150:153]
	v_mfma_f32_16x16x32_bf16 v[68:71], v[174:177], v[64:67], v[0:3]
	v_mfma_f32_16x16x32_bf16 v[0:3], v[12:15], v[178:181], v[154:157]
	v_mfma_f32_16x16x32_bf16 v[44:47], v[24:27], v[182:185], v[0:3]
	v_mfma_f32_16x16x32_bf16 v[0:3], v[170:173], v[178:181], v[158:161]
	v_mfma_f32_16x16x32_bf16 v[36:39], v[174:177], v[182:185], v[0:3]
	v_mfma_f32_16x16x32_bf16 v[0:3], v[12:15], v[210:213], v[162:165]
	v_mfma_f32_16x16x32_bf16 v[28:31], v[24:27], v[214:217], v[0:3]
	v_mfma_f32_16x16x32_bf16 v[0:3], v[170:173], v[210:213], v[166:169]
	v_mfma_f32_16x16x32_bf16 v[20:23], v[174:177], v[214:217], v[0:3]
	v_mfma_f32_16x16x32_bf16 v[0:3], v[12:15], v[230:233], v[8:11]
	v_mfma_f32_16x16x32_bf16 v[12:15], v[24:27], v[234:237], v[0:3]
	v_mfma_f32_16x16x32_bf16 v[0:3], v[170:173], v[230:233], v[202:205]
	v_mfma_f32_16x16x32_bf16 v[4:7], v[174:177], v[234:237], v[0:3]
	v_mfma_f32_16x16x32_bf16 v[0:3], v[190:193], v[40:43], v[16:19]
	v_mfma_f32_16x16x32_bf16 v[72:75], v[194:197], v[64:67], v[0:3]
	v_mfma_f32_16x16x32_bf16 v[0:3], v[198:201], v[40:43], v[206:209]
	v_mfma_f32_16x16x32_bf16 v[64:67], v[226:229], v[64:67], v[0:3]
	v_mfma_f32_16x16x32_bf16 v[0:3], v[190:193], v[178:181], v[32:35]
	v_mfma_f32_16x16x32_bf16 v[40:43], v[194:197], v[182:185], v[0:3]
	v_mfma_f32_16x16x32_bf16 v[0:3], v[198:201], v[178:181], v[218:221]
	v_mfma_f32_16x16x32_bf16 v[32:35], v[226:229], v[182:185], v[0:3]
	v_mfma_f32_16x16x32_bf16 v[0:3], v[190:193], v[210:213], v[222:225]
	v_mfma_f32_16x16x32_bf16 v[24:27], v[194:197], v[214:217], v[0:3]
	v_mfma_f32_16x16x32_bf16 v[0:3], v[198:201], v[210:213], v[186:189]
	v_mfma_f32_16x16x32_bf16 v[16:19], v[226:229], v[214:217], v[0:3]
	v_mfma_f32_16x16x32_bf16 v[0:3], v[190:193], v[230:233], v[130:133]
	v_mfma_f32_16x16x32_bf16 v[8:11], v[194:197], v[234:237], v[0:3]
	v_mfma_f32_16x16x32_bf16 v[0:3], v[198:201], v[230:233], v[140:143]
	v_mfma_f32_16x16x32_bf16 v[0:3], v[226:229], v[234:237], v[0:3]
	s_setprio 0
	s_barrier
	s_andn2_b64 vcc, exec, s[4:5]
	s_cbranch_vccnz .LBB0_888
	s_barrier

; #define PG8_STAGE(bufoff, gbase, voff) do { _Pragma("unroll") for (int _i = 0; _i < 2; ++_i) \
;         __builtin_amdgcn_global_load_lds((const unsigned*)((const char*)(gbase) + (voff)[_i]), (PG8_LAS unsigned*)(lds + (bufoff) + ldsw + _i * 8192), 16, 0, 0); } while (0)
; #define PG8_LDA(dst, b, h) do { _Pragma("unroll") for (int m = 0; m < 4; ++m) _Pragma("unroll") for (int k = 0; k < 2; ++k) dst[m][k] = *(const PG8_LAS bf16x8*)(lds + PG8_SA(b, h) + aoff + m * 2048 + k * 1024); } while (0)
; #define PG8_LDB(dst, b, h) do { _Pragma("unroll") for (int n = 0; n < 2; ++n) _Pragma("unroll") for (int k = 0; k < 2; ++k) dst[n][k] = *(const PG8_LAS bf16x8*)(lds + PG8_SB(b, h) + boff + n * 2048 + k * 1024); } while (0)
; #define PG8_MMA(ai, bj, At, Bt) do { __builtin_amdgcn_s_setprio(1); _Pragma("unroll") for (int m = 0; m < 4; ++m) _Pragma("unroll") for (int n = 0; n < 2; ++n) _Pragma("unroll") for (int k = 0; k < 2; ++k) \
;         acc[ai][bj][m][n] = __builtin_amdgcn_mfma_f32_16x16x32_bf16(Bt[n][k], At[m][k], acc[ai][bj][m][n], 0, 0, 0); __builtin_amdgcn_s_setprio(0); } while (0)
; #define PG8_WAIT_V(n) asm volatile("s_waitcnt vmcnt(" #n ")" ::: "memory")
; #define PG8_WAIT_L(n) asm volatile("s_waitcnt lgkmcnt(" #n ")" ::: "memory")
; template <class Epi, class Sched, bool ALIGN_EPI = false, bool SP2 = false>
; __device__ __forceinline__ void gemm_phase(PG8_LAS unsigned char* lds, const Gemm g, const Sched& S, const Epi& E, int wid_in) {
;     ...
;         for (int t = 0; t < nt; t += 2) {
;             const bool last = (t == nt - 2);
;             if constexpr (Epi::HAS_MID) { if (t == nt / 2) E.mid(acc, cur, wr, wc, fr, fq); }
;             const char* a1 = cA + (size_t)(t + 1) * kstep;
;             const char* a2 = last ? nA : cA + (size_t)(t + 2) * kstep; const char* b2 = last ? nB : cB + (size_t)(t + 2) * kstep;
;             const char* a3 = a2 + kstep; const char* b3 = b2 + kstep;
;             if (last && has_next) S.a_ready(nxt);
;             if constexpr (SP2) {
;             PG8_LDB(B0, 0, 0); PG8_LDB(B1, 0, 1); PG8_SCHED; PG8_LDA(At, 0, 0); PG8_STAGE(PG8_SA(1, 1), a1 + hstep, voffA);
;             PG8_WAIT_V(8); PG8_WAIT_L(0); PG8_BAR; PG8_MMA(0, 0, At, B0); PG8_MMA(0, 1, At, B1); PG8_BAR; PG8_SCHED;
;             PG8_LDA(At, 0, 1); PG8_STAGE(PG8_SB(0, 0), b2, voffB); PG8_STAGE(PG8_SB(0, 1), b2 + hstep, voffB); PG8_STAGE(PG8_SA(0, 0), a2, voffA);
.LBB0_986:
	v_add_u32_e32 v155, s43, v153
	ds_read_b128 v[156:159], v155
	ds_read_b128 v[160:163], v155 offset:1024
	ds_read_b128 v[164:167], v155 offset:2048
	ds_read_b128 v[168:171], v155 offset:3072
	v_add_u32_e32 v155, s44, v153
	s_add_u32 s28, s10, s26
	ds_read_b128 v[172:175], v155
	ds_read_b128 v[176:179], v155 offset:1024
	ds_read_b128 v[180:183], v155 offset:2048
	ds_read_b128 v[184:187], v155 offset:3072
	s_addc_u32 s29, s11, s27
	s_add_u32 s28, s28, 0x100
	s_addc_u32 s29, s29, 0
	s_add_u32 s49, s23, s26
	s_addc_u32 s50, s45, s27
	s_cmpk_eq_i32 s26, 0x700
	s_cselect_b32 s31, s19, s29
	s_cselect_b32 s30, s46, s28
	s_cselect_b32 s29, s17, s50
	s_cselect_b32 s28, s47, s49
	v_lshl_add_u64 v[220:221], v[144:145], 0, s[26:27]
	s_add_i32 m0, s36, 0xc000
	ds_read_b128 v[188:191], v154
	ds_read_b128 v[192:195], v154 offset:1024
	ds_read_b128 v[196:199], v154 offset:2048
	ds_read_b128 v[200:203], v154 offset:3072
	ds_read_b128 v[204:207], v154 offset:4096
	ds_read_b128 v[208:211], v154 offset:5120
	ds_read_b128 v[212:215], v154 offset:6144
	ds_read_b128 v[216:219], v154 offset:7168
	global_load_lds_dwordx4 v[220:221], off
	v_lshl_add_u64 v[220:221], v[146:147], 0, s[26:27]
	s_add_i32 m0, s36, 0xe000
	s_nop 0
	global_load_lds_dwordx4 v[220:221], off
	s_waitcnt vmcnt(8)
	s_waitcnt lgkmcnt(0)
	s_barrier
	s_setprio 1
	v_mfma_f32_16x16x32_bf16 v[60:63], v[156:159], v[188:191], v[60:63]
	v_mfma_f32_16x16x32_bf16 v[56:59], v[164:167], v[188:191], v[56:59]
	v_mfma_f32_16x16x32_bf16 v[88:91], v[156:159], v[196:199], v[88:91]
	v_mfma_f32_16x16x32_bf16 v[84:87], v[164:167], v[196:199], v[84:87]
	v_mfma_f32_16x16x32_bf16 v[108:111], v[156:159], v[204:207], v[108:111]
	v_mfma_f32_16x16x32_bf16 v[104:107], v[164:167], v[204:207], v[104:107]
	v_mfma_f32_16x16x32_bf16 v[124:127], v[156:159], v[212:215], v[124:127]
	v_mfma_f32_16x16x32_bf16 v[120:123], v[164:167], v[212:215], v[120:123]
	v_mfma_f32_16x16x32_bf16 v[60:63], v[160:163], v[192:195], v[60:63]
	v_mfma_f32_16x16x32_bf16 v[56:59], v[168:171], v[192:195], v[56:59]
	v_mfma_f32_16x16x32_bf16 v[88:91], v[160:163], v[200:203], v[88:91]
	v_mfma_f32_16x16x32_bf16 v[84:87], v[168:171], v[200:203], v[84:87]
	v_mfma_f32_16x16x32_bf16 v[108:111], v[160:163], v[208:211], v[108:111]
	v_mfma_f32_16x16x32_bf16 v[104:107], v[168:171], v[208:211], v[104:107]
	v_mfma_f32_16x16x32_bf16 v[124:127], v[160:163], v[216:219], v[124:127]
	v_mfma_f32_16x16x32_bf16 v[120:123], v[168:171], v[216:219], v[120:123]
	v_mfma_f32_16x16x32_bf16 v[36:39], v[172:175], v[188:191], v[36:39]
	v_mfma_f32_16x16x32_bf16 v[32:35], v[180:183], v[188:191], v[32:35]
	v_mfma_f32_16x16x32_bf16 v[68:71], v[172:175], v[196:199], v[68:71]
	v_mfma_f32_16x16x32_bf16 v[64:67], v[180:183], v[196:199], v[64:67]
	v_mfma_f32_16x16x32_bf16 v[100:103], v[172:175], v[204:207], v[100:103]
	v_mfma_f32_16x16x32_bf16 v[96:99], v[180:183], v[204:207], v[96:99]
	v_mfma_f32_16x16x32_bf16 v[116:119], v[172:175], v[212:215], v[116:119]
	v_mfma_f32_16x16x32_bf16 v[112:115], v[180:183], v[212:215], v[112:115]
	v_mfma_f32_16x16x32_bf16 v[36:39], v[176:179], v[192:195], v[36:39]
	v_mfma_f32_16x16x32_bf16 v[32:35], v[184:187], v[192:195], v[32:35]
	v_mfma_f32_16x16x32_bf16 v[68:71], v[176:179], v[200:203], v[68:71]
	v_mfma_f32_16x16x32_bf16 v[64:67], v[184:187], v[200:203], v[64:67]
	v_mfma_f32_16x16x32_bf16 v[100:103], v[176:179], v[208:211], v[100:103]
	v_mfma_f32_16x16x32_bf16 v[96:99], v[184:187], v[208:211], v[96:99]
	v_mfma_f32_16x16x32_bf16 v[116:119], v[176:179], v[216:219], v[116:119]
	v_mfma_f32_16x16x32_bf16 v[112:115], v[184:187], v[216:219], v[112:115]
	s_setprio 0
	s_barrier
	s_add_i32 s49, s43, s35
	v_lshl_add_u64 v[220:221], s[28:29], 0, v[130:131]
	s_mov_b32 m0, s49
	ds_read_b128 v[188:191], v154 offset:16384
	ds_read_b128 v[192:195], v154 offset:17408
	ds_read_b128 v[196:199], v154 offset:18432
	ds_read_b128 v[200:203], v154 offset:19456
	ds_read_b128 v[204:207], v154 offset:20480
	ds_read_b128 v[208:211], v154 offset:21504
	ds_read_b128 v[212:215], v154 offset:22528
	ds_read_b128 v[216:219], v154 offset:23552
	global_load_lds_dwordx4 v[220:221], off
	s_add_i32 m0, s49, 0x2000
	s_add_u32 s50, s28, 0x40000
	v_lshl_add_u64 v[222:223], s[28:29], 0, v[134:135]
	s_addc_u32 s51, s29, 0
	s_add_i32 s49, s44, s35
	global_load_lds_dwordx4 v[222:223], off
	v_lshl_add_u64 v[224:225], s[50:51], 0, v[130:131]
	s_mov_b32 m0, s49
	v_lshl_add_u64 v[226:227], s[30:31], 0, v[132:133]
	global_load_lds_dwordx4 v[224:225], off
	v_lshl_add_u64 v[224:225], s[50:51], 0, v[134:135]
	s_add_i32 m0, s49, 0x2000
	s_nop 0
	global_load_lds_dwordx4 v[224:225], off
	v_lshl_add_u64 v[224:225], s[30:31], 0, v[128:129]
	s_mov_b32 m0, s36
	s_nop 0
	global_load_lds_dwordx4 v[224:225], off
	s_mov_b32 m0, s37
	s_nop 0
	global_load_lds_dwordx4 v[226:227], off
	s_waitcnt vmcnt(8)
	s_waitcnt lgkmcnt(0)
	s_barrier
; #define PG8_STAGE(bufoff, gbase, voff) do { _Pragma("unroll") for (int _i = 0; _i < 2; ++_i) \
;         __builtin_amdgcn_global_load_lds((const unsigned*)((const char*)(gbase) + (voff)[_i]), (PG8_LAS unsigned*)(lds + (bufoff) + ldsw + _i * 8192), 16, 0, 0); } while (0)
; #define PG8_LDA(dst, b, h) do { _Pragma("unroll") for (int m = 0; m < 4; ++m) _Pragma("unroll") for (int k = 0; k < 2; ++k) dst[m][k] = *(const PG8_LAS bf16x8*)(lds + PG8_SA(b, h) + aoff + m * 2048 + k * 1024); } while (0)
; #define PG8_LDB(dst, b, h) do { _Pragma("unroll") for (int n = 0; n < 2; ++n) _Pragma("unroll") for (int k = 0; k < 2; ++k) dst[n][k] = *(const PG8_LAS bf16x8*)(lds + PG8_SB(b, h) + boff + n * 2048 + k * 1024); } while (0)
; #define PG8_MMA(ai, bj, At, Bt) do { __builtin_amdgcn_s_setprio(1); _Pragma("unroll") for (int m = 0; m < 4; ++m) _Pragma("unroll") for (int n = 0; n < 2; ++n) _Pragma("unroll") for (int k = 0; k < 2; ++k) \
;         acc[ai][bj][m][n] = __builtin_amdgcn_mfma_f32_16x16x32_bf16(Bt[n][k], At[m][k], acc[ai][bj][m][n], 0, 0, 0); __builtin_amdgcn_s_setprio(0); } while (0)
; #define PG8_WAIT_V(n) asm volatile("s_waitcnt vmcnt(" #n ")" ::: "memory")
; #define PG8_WAIT_L(n) asm volatile("s_waitcnt lgkmcnt(" #n ")" ::: "memory")
; #define PG8_BAR __builtin_amdgcn_s_barrier()
; #define PG8_SCHED __builtin_amdgcn_sched_barrier(0)
; template <class Epi, class Sched, bool ALIGN_EPI = false, bool SP2 = false>
; __device__ __forceinline__ void gemm_phase(PG8_LAS unsigned char* lds, const Gemm g, const Sched& S, const Epi& E, int wid_in) {
;     ...
;             PG8_WAIT_V(8); PG8_WAIT_L(0); PG8_BAR; PG8_MMA(1, 0, At, B0); PG8_MMA(1, 1, At, B1); PG8_BAR; PG8_SCHED;
;             PG8_LDB(B0, 1, 0); PG8_LDB(B1, 1, 1); PG8_SCHED; PG8_LDA(At, 1, 0); PG8_STAGE(PG8_SA(0, 1), a2 + hstep, voffA);
;             PG8_WAIT_V(8); PG8_WAIT_L(0); PG8_BAR; PG8_MMA(0, 0, At, B0); PG8_MMA(0, 1, At, B1); PG8_BAR; PG8_SCHED;
;             PG8_LDA(At, 1, 1); PG8_STAGE(PG8_SB(1, 0), b3, voffB); PG8_STAGE(PG8_SB(1, 1), b3 + hstep, voffB); PG8_STAGE(PG8_SA(1, 0), a3, voffA);
	s_setprio 1
	v_mfma_f32_16x16x32_bf16 v[92:95], v[156:159], v[188:191], v[92:95]
	v_mfma_f32_16x16x32_bf16 v[80:83], v[164:167], v[188:191], v[80:83]
	v_mfma_f32_16x16x32_bf16 v[52:55], v[156:159], v[196:199], v[52:55]
	v_mfma_f32_16x16x32_bf16 v[48:51], v[164:167], v[196:199], v[48:51]
	v_mfma_f32_16x16x32_bf16 v[28:31], v[156:159], v[204:207], v[28:31]
	v_mfma_f32_16x16x32_bf16 v[24:27], v[164:167], v[204:207], v[24:27]
	v_mfma_f32_16x16x32_bf16 v[12:15], v[156:159], v[212:215], v[12:15]
	v_mfma_f32_16x16x32_bf16 v[8:11], v[164:167], v[212:215], v[8:11]
	v_mfma_f32_16x16x32_bf16 v[92:95], v[160:163], v[192:195], v[92:95]
	v_mfma_f32_16x16x32_bf16 v[80:83], v[168:171], v[192:195], v[80:83]
	v_mfma_f32_16x16x32_bf16 v[52:55], v[160:163], v[200:203], v[52:55]
	v_mfma_f32_16x16x32_bf16 v[48:51], v[168:171], v[200:203], v[48:51]
	v_mfma_f32_16x16x32_bf16 v[28:31], v[160:163], v[208:211], v[28:31]
	v_mfma_f32_16x16x32_bf16 v[24:27], v[168:171], v[208:211], v[24:27]
	v_mfma_f32_16x16x32_bf16 v[12:15], v[160:163], v[216:219], v[12:15]
	v_mfma_f32_16x16x32_bf16 v[8:11], v[168:171], v[216:219], v[8:11]
	v_mfma_f32_16x16x32_bf16 v[76:79], v[172:175], v[188:191], v[76:79]
	v_mfma_f32_16x16x32_bf16 v[72:75], v[180:183], v[188:191], v[72:75]
	v_mfma_f32_16x16x32_bf16 v[44:47], v[172:175], v[196:199], v[44:47]
	v_mfma_f32_16x16x32_bf16 v[40:43], v[180:183], v[196:199], v[40:43]
	v_mfma_f32_16x16x32_bf16 v[20:23], v[172:175], v[204:207], v[20:23]
	v_mfma_f32_16x16x32_bf16 v[16:19], v[180:183], v[204:207], v[16:19]
	v_mfma_f32_16x16x32_bf16 v[4:7], v[172:175], v[212:215], v[4:7]
	v_mfma_f32_16x16x32_bf16 v[0:3], v[180:183], v[212:215], v[0:3]
	v_mfma_f32_16x16x32_bf16 v[76:79], v[176:179], v[192:195], v[76:79]
	v_mfma_f32_16x16x32_bf16 v[72:75], v[184:187], v[192:195], v[72:75]
	v_mfma_f32_16x16x32_bf16 v[44:47], v[176:179], v[200:203], v[44:47]
	v_mfma_f32_16x16x32_bf16 v[40:43], v[184:187], v[200:203], v[40:43]
	v_mfma_f32_16x16x32_bf16 v[20:23], v[176:179], v[208:211], v[20:23]
	v_mfma_f32_16x16x32_bf16 v[16:19], v[184:187], v[208:211], v[16:19]
	v_mfma_f32_16x16x32_bf16 v[4:7], v[176:179], v[216:219], v[4:7]
	v_mfma_f32_16x16x32_bf16 v[0:3], v[184:187], v[216:219], v[0:3]
	s_setprio 0
	s_barrier
	s_add_i32 s49, 0, 0x18000
	v_add_u32_e32 v155, s49, v153
	s_add_i32 s50, 0, 0x1c000
	ds_read_b128 v[156:159], v155
	ds_read_b128 v[160:163], v155 offset:1024
	ds_read_b128 v[164:167], v155 offset:2048
	ds_read_b128 v[168:171], v155 offset:3072
	v_add_u32_e32 v155, s50, v153
	ds_read_b128 v[172:175], v155
	ds_read_b128 v[176:179], v155 offset:1024
	ds_read_b128 v[180:183], v155 offset:2048
	ds_read_b128 v[184:187], v155 offset:3072
	s_add_u32 s30, s30, 0x40000
	s_addc_u32 s31, s31, 0
	s_mov_b32 m0, s38
	v_lshl_add_u64 v[228:229], s[30:31], 0, v[128:129]
	ds_read_b128 v[188:191], v154 offset:32768
	ds_read_b128 v[192:195], v154 offset:33792
	ds_read_b128 v[196:199], v154 offset:34816
	ds_read_b128 v[200:203], v154 offset:35840
	ds_read_b128 v[204:207], v154 offset:36864
	ds_read_b128 v[208:211], v154 offset:37888
	ds_read_b128 v[212:215], v154 offset:38912
	ds_read_b128 v[216:219], v154 offset:39936
	global_load_lds_dwordx4 v[228:229], off
	v_lshl_add_u64 v[228:229], s[30:31], 0, v[132:133]
	s_mov_b32 m0, s39
	s_nop 0
	global_load_lds_dwordx4 v[228:229], off
	s_waitcnt vmcnt(8)
	s_waitcnt lgkmcnt(0)
	s_barrier
	s_setprio 1
	v_mfma_f32_16x16x32_bf16 v[60:63], v[156:159], v[188:191], v[60:63]
	v_mfma_f32_16x16x32_bf16 v[56:59], v[164:167], v[188:191], v[56:59]
	v_mfma_f32_16x16x32_bf16 v[88:91], v[156:159], v[196:199], v[88:91]
	v_mfma_f32_16x16x32_bf16 v[84:87], v[164:167], v[196:199], v[84:87]
	v_mfma_f32_16x16x32_bf16 v[108:111], v[156:159], v[204:207], v[108:111]
	v_mfma_f32_16x16x32_bf16 v[104:107], v[164:167], v[204:207], v[104:107]
	v_mfma_f32_16x16x32_bf16 v[124:127], v[156:159], v[212:215], v[124:127]
	v_mfma_f32_16x16x32_bf16 v[120:123], v[164:167], v[212:215], v[120:123]
	v_mfma_f32_16x16x32_bf16 v[60:63], v[160:163], v[192:195], v[60:63]
	v_mfma_f32_16x16x32_bf16 v[56:59], v[168:171], v[192:195], v[56:59]
	v_mfma_f32_16x16x32_bf16 v[88:91], v[160:163], v[200:203], v[88:91]
	v_mfma_f32_16x16x32_bf16 v[84:87], v[168:171], v[200:203], v[84:87]
	v_mfma_f32_16x16x32_bf16 v[108:111], v[160:163], v[208:211], v[108:111]
	v_mfma_f32_16x16x32_bf16 v[104:107], v[168:171], v[208:211], v[104:107]
	v_mfma_f32_16x16x32_bf16 v[124:127], v[160:163], v[216:219], v[124:127]
	v_mfma_f32_16x16x32_bf16 v[120:123], v[168:171], v[216:219], v[120:123]
	v_mfma_f32_16x16x32_bf16 v[36:39], v[172:175], v[188:191], v[36:39]
	v_mfma_f32_16x16x32_bf16 v[32:35], v[180:183], v[188:191], v[32:35]
	v_mfma_f32_16x16x32_bf16 v[68:71], v[172:175], v[196:199], v[68:71]
	v_mfma_f32_16x16x32_bf16 v[64:67], v[180:183], v[196:199], v[64:67]
	v_mfma_f32_16x16x32_bf16 v[100:103], v[172:175], v[204:207], v[100:103]
	v_mfma_f32_16x16x32_bf16 v[96:99], v[180:183], v[204:207], v[96:99]
	v_mfma_f32_16x16x32_bf16 v[116:119], v[172:175], v[212:215], v[116:119]
	v_mfma_f32_16x16x32_bf16 v[112:115], v[180:183], v[212:215], v[112:115]
	v_mfma_f32_16x16x32_bf16 v[36:39], v[176:179], v[192:195], v[36:39]
	v_mfma_f32_16x16x32_bf16 v[32:35], v[184:187], v[192:195], v[32:35]
	v_mfma_f32_16x16x32_bf16 v[68:71], v[176:179], v[200:203], v[68:71]
	v_mfma_f32_16x16x32_bf16 v[64:67], v[184:187], v[200:203], v[64:67]
	v_mfma_f32_16x16x32_bf16 v[100:103], v[176:179], v[208:211], v[100:103]
	v_mfma_f32_16x16x32_bf16 v[96:99], v[184:187], v[208:211], v[96:99]
	v_mfma_f32_16x16x32_bf16 v[116:119], v[176:179], v[216:219], v[116:119]
	v_mfma_f32_16x16x32_bf16 v[112:115], v[184:187], v[216:219], v[112:115]
	s_setprio 0
	s_barrier
; #define PG8_STAGE(bufoff, gbase, voff) do { _Pragma("unroll") for (int _i = 0; _i < 2; ++_i) \
;         __builtin_amdgcn_global_load_lds((const unsigned*)((const char*)(gbase) + (voff)[_i]), (PG8_LAS unsigned*)(lds + (bufoff) + ldsw + _i * 8192), 16, 0, 0); } while (0)
; #define PG8_LDA(dst, b, h) do { _Pragma("unroll") for (int m = 0; m < 4; ++m) _Pragma("unroll") for (int k = 0; k < 2; ++k) dst[m][k] = *(const PG8_LAS bf16x8*)(lds + PG8_SA(b, h) + aoff + m * 2048 + k * 1024); } while (0)
; #define PG8_MMA(ai, bj, At, Bt) do { __builtin_amdgcn_s_setprio(1); _Pragma("unroll") for (int m = 0; m < 4; ++m) _Pragma("unroll") for (int n = 0; n < 2; ++n) _Pragma("unroll") for (int k = 0; k < 2; ++k) \
;         acc[ai][bj][m][n] = __builtin_amdgcn_mfma_f32_16x16x32_bf16(Bt[n][k], At[m][k], acc[ai][bj][m][n], 0, 0, 0); __builtin_amdgcn_s_setprio(0); } while (0)
; #define PG8_WAIT_V(n) asm volatile("s_waitcnt vmcnt(" #n ")" ::: "memory")
; #define PG8_WAIT_L(n) asm volatile("s_waitcnt lgkmcnt(" #n ")" ::: "memory")
; #define PG8_BAR __builtin_amdgcn_s_barrier()
; #define PG8_SCHED __builtin_amdgcn_sched_barrier(0)
; template <class Epi, class Sched, bool ALIGN_EPI = false, bool SP2 = false>
; __device__ __forceinline__ void gemm_phase(PG8_LAS unsigned char* lds, const Gemm g, const Sched& S, const Epi& E, int wid_in) {
;     ...
;             PG8_LDA(At, 1, 1); PG8_STAGE(PG8_SB(1, 0), b3, voffB); PG8_STAGE(PG8_SB(1, 1), b3 + hstep, voffB); PG8_STAGE(PG8_SA(1, 0), a3, voffA);
;             PG8_WAIT_V(8); PG8_WAIT_L(0); PG8_BAR; PG8_MMA(1, 0, At, B0); PG8_MMA(1, 1, At, B1); PG8_BAR; PG8_SCHED;
;     ...
;         if (!has_next) break;
; #pragma unroll
;         for (int a = 0; a < 2; ++a)
; #pragma unroll
;             for (int b = 0; b < 2; ++b)
; #pragma unroll
;                 for (int m = 0; m < 4; ++m)
; #pragma unroll
;                     for (int n = 0; n < 2; ++n) acc[a][b][m][n] = (f32x4){0.f, 0.f, 0.f, 0.f};
	s_add_i32 s30, s49, s35
	v_lshl_add_u64 v[220:221], v[220:221], 0, s[14:15]
	s_mov_b32 m0, s30
	ds_read_b128 v[188:191], v154 offset:49152
	ds_read_b128 v[192:195], v154 offset:50176
	ds_read_b128 v[196:199], v154 offset:51200
	ds_read_b128 v[200:203], v154 offset:52224
	ds_read_b128 v[204:207], v154 offset:53248
	ds_read_b128 v[208:211], v154 offset:54272
	ds_read_b128 v[212:215], v154 offset:55296
	ds_read_b128 v[216:219], v154 offset:56320
	global_load_lds_dwordx4 v[220:221], off
	s_add_i32 m0, s30, 0x2000
	s_add_u32 s28, s28, 0x40080
	v_lshl_add_u64 v[220:221], v[222:223], 0, s[14:15]
	s_addc_u32 s29, s29, 0
	s_add_i32 s30, s50, s35
	global_load_lds_dwordx4 v[220:221], off
	v_lshl_add_u64 v[220:221], s[28:29], 0, v[130:131]
	s_mov_b32 m0, s30
	s_nop 0
	global_load_lds_dwordx4 v[220:221], off
	v_lshl_add_u64 v[220:221], s[28:29], 0, v[134:135]
	s_add_i32 m0, s30, 0x2000
	s_nop 0
	global_load_lds_dwordx4 v[220:221], off
	v_lshl_add_u64 v[220:221], v[224:225], 0, s[14:15]
	s_mov_b32 m0, s41
	s_nop 0
	global_load_lds_dwordx4 v[220:221], off
	v_lshl_add_u64 v[220:221], v[226:227], 0, s[14:15]
	s_mov_b32 m0, s42
	s_nop 0
	global_load_lds_dwordx4 v[220:221], off
	s_waitcnt vmcnt(8)
	s_waitcnt lgkmcnt(0)
	s_barrier
	s_setprio 1
	v_mfma_f32_16x16x32_bf16 v[92:95], v[156:159], v[188:191], v[92:95]
	v_mfma_f32_16x16x32_bf16 v[80:83], v[164:167], v[188:191], v[80:83]
	v_mfma_f32_16x16x32_bf16 v[52:55], v[156:159], v[196:199], v[52:55]
	v_mfma_f32_16x16x32_bf16 v[48:51], v[164:167], v[196:199], v[48:51]
	v_mfma_f32_16x16x32_bf16 v[28:31], v[156:159], v[204:207], v[28:31]
	v_mfma_f32_16x16x32_bf16 v[24:27], v[164:167], v[204:207], v[24:27]
	v_mfma_f32_16x16x32_bf16 v[12:15], v[156:159], v[212:215], v[12:15]
	v_mfma_f32_16x16x32_bf16 v[8:11], v[164:167], v[212:215], v[8:11]
	v_mfma_f32_16x16x32_bf16 v[92:95], v[160:163], v[192:195], v[92:95]
	v_mfma_f32_16x16x32_bf16 v[80:83], v[168:171], v[192:195], v[80:83]
	v_mfma_f32_16x16x32_bf16 v[52:55], v[160:163], v[200:203], v[52:55]
	v_mfma_f32_16x16x32_bf16 v[48:51], v[168:171], v[200:203], v[48:51]
	v_mfma_f32_16x16x32_bf16 v[28:31], v[160:163], v[208:211], v[28:31]
	v_mfma_f32_16x16x32_bf16 v[24:27], v[168:171], v[208:211], v[24:27]
	v_mfma_f32_16x16x32_bf16 v[12:15], v[160:163], v[216:219], v[12:15]
	v_mfma_f32_16x16x32_bf16 v[8:11], v[168:171], v[216:219], v[8:11]
	v_mfma_f32_16x16x32_bf16 v[76:79], v[172:175], v[188:191], v[76:79]
	v_mfma_f32_16x16x32_bf16 v[72:75], v[180:183], v[188:191], v[72:75]
	v_mfma_f32_16x16x32_bf16 v[44:47], v[172:175], v[196:199], v[44:47]
	v_mfma_f32_16x16x32_bf16 v[40:43], v[180:183], v[196:199], v[40:43]
	v_mfma_f32_16x16x32_bf16 v[20:23], v[172:175], v[204:207], v[20:23]
	v_mfma_f32_16x16x32_bf16 v[16:19], v[180:183], v[204:207], v[16:19]
	v_mfma_f32_16x16x32_bf16 v[4:7], v[172:175], v[212:215], v[4:7]
	v_mfma_f32_16x16x32_bf16 v[0:3], v[180:183], v[212:215], v[0:3]
	v_mfma_f32_16x16x32_bf16 v[76:79], v[176:179], v[192:195], v[76:79]
	v_mfma_f32_16x16x32_bf16 v[72:75], v[184:187], v[192:195], v[72:75]
	v_mfma_f32_16x16x32_bf16 v[44:47], v[176:179], v[200:203], v[44:47]
	v_mfma_f32_16x16x32_bf16 v[40:43], v[184:187], v[200:203], v[40:43]
	v_mfma_f32_16x16x32_bf16 v[20:23], v[176:179], v[208:211], v[20:23]
	v_mfma_f32_16x16x32_bf16 v[16:19], v[184:187], v[208:211], v[16:19]
	v_mfma_f32_16x16x32_bf16 v[4:7], v[176:179], v[216:219], v[4:7]
	v_mfma_f32_16x16x32_bf16 v[0:3], v[184:187], v[216:219], v[0:3]
	s_setprio 0
	s_barrier
	s_add_i32 s48, s48, 2
	s_add_u32 s26, s26, 0x100
	s_addc_u32 s27, s27, 0
	s_cmp_gt_u32 s48, 13
	s_cbranch_scc0 .LBB0_986
	s_add_u32 s26, s23, 0xffffff00
	s_addc_u32 s27, s45, -1
	s_andn2_b64 vcc, exec, s[2:3]
	s_cbranch_vccnz .LBB0_977
	v_mov_b32_e32 v0, 0
	s_mov_b32 s6, s16
	s_mov_b32 s4, s18
	s_mov_b64 s[10:11], s[24:25]
	s_mov_b32 s40, s22
	v_mov_b32_e32 v1, v0
	v_mov_b32_e32 v2, v0
	v_mov_b32_e32 v3, v0
	v_mov_b32_e32 v4, v0
	v_mov_b32_e32 v5, v0
	v_mov_b32_e32 v6, v0
	v_mov_b32_e32 v7, v0
	v_mov_b32_e32 v16, v0
	v_mov_b32_e32 v17, v0
	v_mov_b32_e32 v18, v0
	v_mov_b32_e32 v19, v0
	v_mov_b32_e32 v20, v0
	v_mov_b32_e32 v21, v0
	v_mov_b32_e32 v22, v0
	v_mov_b32_e32 v23, v0
	v_mov_b32_e32 v40, v0
	v_mov_b32_e32 v41, v0
	v_mov_b32_e32 v42, v0
	v_mov_b32_e32 v43, v0
	v_mov_b32_e32 v44, v0
	v_mov_b32_e32 v45, v0
	v_mov_b32_e32 v46, v0
	v_mov_b32_e32 v47, v0
	v_mov_b32_e32 v72, v0
	v_mov_b32_e32 v73, v0
	v_mov_b32_e32 v74, v0
	v_mov_b32_e32 v75, v0
	v_mov_b32_e32 v76, v0
	v_mov_b32_e32 v77, v0
	v_mov_b32_e32 v78, v0
	v_mov_b32_e32 v79, v0
	v_mov_b32_e32 v8, v0
	v_mov_b32_e32 v9, v0
	v_mov_b32_e32 v10, v0
	v_mov_b32_e32 v11, v0
	v_mov_b32_e32 v12, v0
	v_mov_b32_e32 v13, v0
	v_mov_b32_e32 v14, v0
	v_mov_b32_e32 v15, v0
	v_mov_b32_e32 v24, v0
	v_mov_b32_e32 v25, v0
	v_mov_b32_e32 v26, v0
	v_mov_b32_e32 v27, v0
	v_mov_b32_e32 v28, v0
	v_mov_b32_e32 v29, v0
	v_mov_b32_e32 v30, v0
	v_mov_b32_e32 v31, v0
	v_mov_b32_e32 v48, v0
	v_mov_b32_e32 v49, v0
	v_mov_b32_e32 v50, v0
	v_mov_b32_e32 v51, v0
	v_mov_b32_e32 v52, v0
	v_mov_b32_e32 v53, v0
	v_mov_b32_e32 v54, v0
	v_mov_b32_e32 v55, v0
	v_mov_b32_e32 v80, v0
	v_mov_b32_e32 v81, v0
	v_mov_b32_e32 v82, v0
	v_mov_b32_e32 v83, v0
	v_mov_b32_e32 v92, v0
	v_mov_b32_e32 v93, v0
	v_mov_b32_e32 v94, v0
	v_mov_b32_e32 v95, v0
	v_mov_b32_e32 v112, v0
	v_mov_b32_e32 v113, v0
	v_mov_b32_e32 v114, v0
	v_mov_b32_e32 v115, v0
	v_mov_b32_e32 v116, v0
	v_mov_b32_e32 v117, v0
	v_mov_b32_e32 v118, v0
	v_mov_b32_e32 v119, v0
	v_mov_b32_e32 v96, v0
	v_mov_b32_e32 v97, v0
	v_mov_b32_e32 v98, v0
	v_mov_b32_e32 v99, v0
	v_mov_b32_e32 v100, v0
	v_mov_b32_e32 v101, v0
	v_mov_b32_e32 v102, v0
	v_mov_b32_e32 v103, v0
	v_mov_b32_e32 v64, v0
	v_mov_b32_e32 v65, v0
	v_mov_b32_e32 v66, v0
	v_mov_b32_e32 v67, v0
	v_mov_b32_e32 v68, v0
	v_mov_b32_e32 v69, v0
	v_mov_b32_e32 v70, v0
	v_mov_b32_e32 v71, v0
	v_mov_b32_e32 v32, v0
	v_mov_b32_e32 v33, v0
	v_mov_b32_e32 v34, v0
	v_mov_b32_e32 v35, v0
	v_mov_b32_e32 v36, v0
	v_mov_b32_e32 v37, v0
	v_mov_b32_e32 v38, v0
	v_mov_b32_e32 v39, v0
	v_mov_b32_e32 v120, v0
	v_mov_b32_e32 v121, v0
	v_mov_b32_e32 v122, v0
	v_mov_b32_e32 v123, v0
	v_mov_b32_e32 v124, v0
	v_mov_b32_e32 v125, v0
	v_mov_b32_e32 v126, v0
	v_mov_b32_e32 v127, v0
	v_mov_b32_e32 v104, v0
	v_mov_b32_e32 v105, v0
	v_mov_b32_e32 v106, v0
	v_mov_b32_e32 v107, v0
	v_mov_b32_e32 v108, v0
	v_mov_b32_e32 v109, v0
	v_mov_b32_e32 v110, v0
	v_mov_b32_e32 v111, v0
	v_mov_b32_e32 v84, v0
	v_mov_b32_e32 v85, v0
	v_mov_b32_e32 v86, v0
	v_mov_b32_e32 v87, v0
	v_mov_b32_e32 v88, v0
	v_mov_b32_e32 v89, v0
	v_mov_b32_e32 v90, v0
	v_mov_b32_e32 v91, v0
	v_mov_b32_e32 v56, v0
	v_mov_b32_e32 v57, v0
	v_mov_b32_e32 v58, v0
	v_mov_b32_e32 v59, v0
	v_mov_b32_e32 v60, v0
	v_mov_b32_e32 v61, v0
	v_mov_b32_e32 v62, v0
	v_mov_b32_e32 v63, v0
	s_andn2_b64 vcc, exec, s[0:1]
	s_cbranch_vccnz .LBB0_978
